# select phase: the two 16-round max and knock-out loops replaced by sorting networks (odd-even merge sort + bitonic top-16 merges); UC reads consecutive tokens per wave
# speedup vs baseline: 1.1038x; 1.0096x over previous
; DI void peer_half_topk(const bf16_t* qrow  , const bf16_t* subk  , int hi, int lane, LAS unsigned* ltop) {
;     ...
; #pragma unroll 1
;     for (int k = 0; k < 16; ++k) {
;         unsigned mx = keys[0];
; #pragma unroll
;         for (int i = 1; i < 64; ++i) mx = mx > keys[i] ? mx : keys[i];
;         const unsigned om = (unsigned)__shfl_xor((int)mx, 32);
;         mx = mx > om ? mx : om;
;         ltop[k * 64 + lane] = mx;
; #pragma unroll
;         for (int i = 0; i < 64; ++i) keys[i] = keys[i] == mx ? 0u : keys[i];
;     }
.LBB0_41:
	v_max_u32_e32 v16, v128, v49
	v_min_u32_e32 v128, v128, v49
	v_max_u32_e32 v17, v156, v153
	v_min_u32_e32 v156, v156, v153
	v_max_u32_e32 v18, v172, v169
	v_min_u32_e32 v172, v172, v169
	v_max_u32_e32 v19, v0, v1
	v_min_u32_e32 v0, v0, v1
	v_max_u32_e32 v49, v142, v119
	v_min_u32_e32 v142, v142, v119
	v_max_u32_e32 v153, v158, v155
	v_min_u32_e32 v158, v158, v155
	v_max_u32_e32 v169, v174, v171
	v_min_u32_e32 v174, v174, v171
	v_max_u32_e32 v1, v2, v3
	v_min_u32_e32 v2, v2, v3
	v_max_u32_e32 v119, v16, v49
	v_min_u32_e32 v16, v16, v49
	v_max_u32_e32 v155, v17, v153
	v_min_u32_e32 v17, v17, v153
	v_max_u32_e32 v171, v18, v169
	v_min_u32_e32 v18, v18, v169
	v_max_u32_e32 v3, v19, v1
	v_min_u32_e32 v19, v19, v1
	v_max_u32_e32 v49, v128, v142
	v_min_u32_e32 v128, v128, v142
	v_max_u32_e32 v153, v156, v158
	v_min_u32_e32 v156, v156, v158
	v_max_u32_e32 v169, v172, v174
	v_min_u32_e32 v172, v172, v174
	v_max_u32_e32 v1, v0, v2
	v_min_u32_e32 v0, v0, v2
	v_max_u32_e32 v142, v49, v16
	v_min_u32_e32 v49, v49, v16
	v_max_u32_e32 v158, v153, v17
	v_min_u32_e32 v153, v153, v17
	v_max_u32_e32 v174, v169, v18
	v_min_u32_e32 v169, v169, v18
	v_max_u32_e32 v2, v1, v19
	v_min_u32_e32 v1, v1, v19
	v_max_u32_e32 v16, v144, v131
	v_min_u32_e32 v144, v144, v131
	v_max_u32_e32 v17, v160, v157
	v_min_u32_e32 v160, v160, v157
	v_max_u32_e32 v18, v176, v173
	v_min_u32_e32 v176, v176, v173
	v_max_u32_e32 v19, v4, v5
	v_min_u32_e32 v4, v4, v5
	v_max_u32_e32 v131, v146, v143
	v_min_u32_e32 v146, v146, v143
	v_max_u32_e32 v157, v162, v159
	v_min_u32_e32 v162, v162, v159
	v_max_u32_e32 v173, v178, v175
	v_min_u32_e32 v178, v178, v175
	v_max_u32_e32 v5, v6, v7
	v_min_u32_e32 v6, v6, v7
	v_max_u32_e32 v143, v16, v131
	v_min_u32_e32 v16, v16, v131
	v_max_u32_e32 v159, v17, v157
	v_min_u32_e32 v17, v17, v157
	v_max_u32_e32 v175, v18, v173
	v_min_u32_e32 v18, v18, v173
	v_max_u32_e32 v7, v19, v5
	v_min_u32_e32 v19, v19, v5
	v_max_u32_e32 v131, v144, v146
	v_min_u32_e32 v144, v144, v146
	v_max_u32_e32 v157, v160, v162
	v_min_u32_e32 v160, v160, v162
	v_max_u32_e32 v173, v176, v178
	v_min_u32_e32 v176, v176, v178
	v_max_u32_e32 v5, v4, v6
	v_min_u32_e32 v4, v4, v6
	v_max_u32_e32 v146, v131, v16
	v_min_u32_e32 v131, v131, v16
	v_max_u32_e32 v162, v157, v17
	v_min_u32_e32 v157, v157, v17
	v_max_u32_e32 v178, v173, v18
	v_min_u32_e32 v173, v173, v18
	v_max_u32_e32 v6, v5, v19
	v_min_u32_e32 v5, v5, v19
	v_max_u32_e32 v16, v119, v143
	v_min_u32_e32 v119, v119, v143
	v_max_u32_e32 v17, v155, v159
	v_min_u32_e32 v155, v155, v159
	v_max_u32_e32 v18, v171, v175
	v_min_u32_e32 v171, v171, v175
	v_max_u32_e32 v19, v3, v7
	v_min_u32_e32 v3, v3, v7
	v_max_u32_e32 v143, v49, v131
	v_min_u32_e32 v49, v49, v131
	v_max_u32_e32 v159, v153, v157
	v_min_u32_e32 v153, v153, v157
	v_max_u32_e32 v175, v169, v173
	v_min_u32_e32 v169, v169, v173
	v_max_u32_e32 v7, v1, v5
	v_min_u32_e32 v1, v1, v5
	v_max_u32_e32 v131, v143, v119
	v_min_u32_e32 v143, v143, v119
	v_max_u32_e32 v157, v159, v155
	v_min_u32_e32 v159, v159, v155
	v_max_u32_e32 v173, v175, v171
	v_min_u32_e32 v175, v175, v171
	v_max_u32_e32 v5, v7, v3
	v_min_u32_e32 v7, v7, v3
	v_max_u32_e32 v119, v142, v146
	v_min_u32_e32 v142, v142, v146
	v_max_u32_e32 v155, v158, v162
	v_min_u32_e32 v158, v158, v162
	v_max_u32_e32 v171, v174, v178
	v_min_u32_e32 v174, v174, v178
	v_max_u32_e32 v3, v2, v6
	v_min_u32_e32 v2, v2, v6
	v_max_u32_e32 v146, v128, v144
	v_min_u32_e32 v128, v128, v144
	v_max_u32_e32 v162, v156, v160
	v_min_u32_e32 v156, v156, v160
	v_max_u32_e32 v178, v172, v176
	v_min_u32_e32 v172, v172, v176
	v_max_u32_e32 v6, v0, v4
	v_min_u32_e32 v0, v0, v4
	v_max_u32_e32 v144, v146, v142
	v_min_u32_e32 v146, v146, v142
	v_max_u32_e32 v160, v162, v158
	v_min_u32_e32 v162, v162, v158
	v_max_u32_e32 v176, v178, v174
	v_min_u32_e32 v178, v178, v174
	v_max_u32_e32 v4, v6, v2
	v_min_u32_e32 v6, v6, v2
	v_max_u32_e32 v142, v119, v131
	v_min_u32_e32 v119, v119, v131
	v_max_u32_e32 v158, v155, v157
	v_min_u32_e32 v155, v155, v157
	v_max_u32_e32 v174, v171, v173
	v_min_u32_e32 v171, v171, v173
	v_max_u32_e32 v2, v3, v5
	v_min_u32_e32 v3, v3, v5
	v_max_u32_e32 v131, v144, v143
	v_min_u32_e32 v144, v144, v143
	v_max_u32_e32 v157, v160, v159
	v_min_u32_e32 v160, v160, v159
	v_max_u32_e32 v173, v176, v175
	v_min_u32_e32 v176, v176, v175
	v_max_u32_e32 v5, v4, v7
	v_min_u32_e32 v4, v4, v7
	v_max_u32_e32 v143, v146, v49
	v_min_u32_e32 v146, v146, v49
	v_max_u32_e32 v159, v162, v153
	v_min_u32_e32 v162, v162, v153
	v_max_u32_e32 v175, v178, v169
	v_min_u32_e32 v178, v178, v169
	v_max_u32_e32 v7, v6, v1
	v_min_u32_e32 v6, v6, v1
	v_max_u32_e32 v49, v148, v145
	v_min_u32_e32 v148, v148, v145
	v_max_u32_e32 v153, v164, v161
	v_min_u32_e32 v164, v164, v161
	v_max_u32_e32 v169, v180, v177
	v_min_u32_e32 v180, v180, v177
	v_max_u32_e32 v1, v8, v9
	v_min_u32_e32 v8, v8, v9
	v_max_u32_e32 v145, v150, v147
	v_min_u32_e32 v150, v150, v147
	v_max_u32_e32 v161, v166, v163
	v_min_u32_e32 v166, v166, v163
	v_max_u32_e32 v177, v182, v179
	v_min_u32_e32 v182, v182, v179
	v_max_u32_e32 v9, v10, v11
	v_min_u32_e32 v10, v10, v11
	v_max_u32_e32 v147, v49, v145
	v_min_u32_e32 v49, v49, v145
	v_max_u32_e32 v163, v153, v161
	v_min_u32_e32 v153, v153, v161
	v_max_u32_e32 v179, v169, v177
	v_min_u32_e32 v169, v169, v177
	v_max_u32_e32 v11, v1, v9
	v_min_u32_e32 v1, v1, v9
	v_max_u32_e32 v145, v148, v150
	v_min_u32_e32 v148, v148, v150
	v_max_u32_e32 v161, v164, v166
	v_min_u32_e32 v164, v164, v166
	v_max_u32_e32 v177, v180, v182
	v_min_u32_e32 v180, v180, v182
	v_max_u32_e32 v9, v8, v10
	v_min_u32_e32 v8, v8, v10
	v_max_u32_e32 v150, v145, v49
	v_min_u32_e32 v145, v145, v49
; DI void peer_half_topk(const bf16_t* qrow  , const bf16_t* subk  , int hi, int lane, LAS unsigned* ltop) {
;     ...
; #pragma unroll 1
;     for (int k = 0; k < 16; ++k) {
;         unsigned mx = keys[0];
; #pragma unroll
;         for (int i = 1; i < 64; ++i) mx = mx > keys[i] ? mx : keys[i];
;         const unsigned om = (unsigned)__shfl_xor((int)mx, 32);
;         mx = mx > om ? mx : om;
;         ltop[k * 64 + lane] = mx;
; #pragma unroll
;         for (int i = 0; i < 64; ++i) keys[i] = keys[i] == mx ? 0u : keys[i];
;     }
	v_max_u32_e32 v166, v161, v153
	v_min_u32_e32 v161, v161, v153
	v_max_u32_e32 v182, v177, v169
	v_min_u32_e32 v177, v177, v169
	v_max_u32_e32 v10, v9, v1
	v_min_u32_e32 v9, v9, v1
	v_max_u32_e32 v49, v152, v149
	v_min_u32_e32 v152, v152, v149
	v_max_u32_e32 v153, v168, v165
	v_min_u32_e32 v168, v168, v165
	v_max_u32_e32 v169, v184, v181
	v_min_u32_e32 v184, v184, v181
	v_max_u32_e32 v1, v12, v13
	v_min_u32_e32 v12, v12, v13
	v_max_u32_e32 v149, v154, v151
	v_min_u32_e32 v154, v154, v151
	v_max_u32_e32 v165, v170, v167
	v_min_u32_e32 v170, v170, v167
	v_max_u32_e32 v181, v186, v183
	v_min_u32_e32 v186, v186, v183
	v_max_u32_e32 v13, v14, v15
	v_min_u32_e32 v14, v14, v15
	v_max_u32_e32 v151, v49, v149
	v_min_u32_e32 v49, v49, v149
	v_max_u32_e32 v167, v153, v165
	v_min_u32_e32 v153, v153, v165
	v_max_u32_e32 v183, v169, v181
	v_min_u32_e32 v169, v169, v181
	v_max_u32_e32 v15, v1, v13
	v_min_u32_e32 v1, v1, v13
	v_max_u32_e32 v149, v152, v154
	v_min_u32_e32 v152, v152, v154
	v_max_u32_e32 v165, v168, v170
	v_min_u32_e32 v168, v168, v170
	v_max_u32_e32 v181, v184, v186
	v_min_u32_e32 v184, v184, v186
	v_max_u32_e32 v13, v12, v14
	v_min_u32_e32 v12, v12, v14
	v_max_u32_e32 v154, v149, v49
	v_min_u32_e32 v149, v149, v49
	v_max_u32_e32 v170, v165, v153
	v_min_u32_e32 v165, v165, v153
	v_max_u32_e32 v186, v181, v169
	v_min_u32_e32 v181, v181, v169
	v_max_u32_e32 v14, v13, v1
	v_min_u32_e32 v13, v13, v1
	v_max_u32_e32 v49, v147, v151
	v_min_u32_e32 v147, v147, v151
	v_max_u32_e32 v153, v163, v167
	v_min_u32_e32 v163, v163, v167
	v_max_u32_e32 v169, v179, v183
	v_min_u32_e32 v179, v179, v183
	v_max_u32_e32 v1, v11, v15
	v_min_u32_e32 v11, v11, v15
	v_max_u32_e32 v151, v145, v149
	v_min_u32_e32 v145, v145, v149
	v_max_u32_e32 v167, v161, v165
	v_min_u32_e32 v161, v161, v165
	v_max_u32_e32 v183, v177, v181
	v_min_u32_e32 v177, v177, v181
	v_max_u32_e32 v15, v9, v13
	v_min_u32_e32 v9, v9, v13
	v_max_u32_e32 v149, v151, v147
	v_min_u32_e32 v151, v151, v147
	v_max_u32_e32 v165, v167, v163
	v_min_u32_e32 v167, v167, v163
	v_max_u32_e32 v181, v183, v179
	v_min_u32_e32 v183, v183, v179
	v_max_u32_e32 v13, v15, v11
	v_min_u32_e32 v15, v15, v11
	v_max_u32_e32 v147, v150, v154
	v_min_u32_e32 v150, v150, v154
	v_max_u32_e32 v163, v166, v170
	v_min_u32_e32 v166, v166, v170
	v_max_u32_e32 v179, v182, v186
	v_min_u32_e32 v182, v182, v186
	v_max_u32_e32 v11, v10, v14
	v_min_u32_e32 v10, v10, v14
	v_max_u32_e32 v154, v148, v152
	v_min_u32_e32 v148, v148, v152
	v_max_u32_e32 v170, v164, v168
	v_min_u32_e32 v164, v164, v168
	v_max_u32_e32 v186, v180, v184
	v_min_u32_e32 v180, v180, v184
	v_max_u32_e32 v14, v8, v12
	v_min_u32_e32 v8, v8, v12
	v_max_u32_e32 v152, v154, v150
	v_min_u32_e32 v154, v154, v150
	v_max_u32_e32 v168, v170, v166
	v_min_u32_e32 v170, v170, v166
	v_max_u32_e32 v184, v186, v182
	v_min_u32_e32 v186, v186, v182
	v_max_u32_e32 v12, v14, v10
	v_min_u32_e32 v14, v14, v10
	v_max_u32_e32 v150, v147, v149
	v_min_u32_e32 v147, v147, v149
	v_max_u32_e32 v166, v163, v165
	v_min_u32_e32 v163, v163, v165
	v_max_u32_e32 v182, v179, v181
	v_min_u32_e32 v179, v179, v181
	v_max_u32_e32 v10, v11, v13
	v_min_u32_e32 v11, v11, v13
	v_max_u32_e32 v149, v152, v151
	v_min_u32_e32 v152, v152, v151
	v_max_u32_e32 v165, v168, v167
	v_min_u32_e32 v168, v168, v167
	v_max_u32_e32 v181, v184, v183
	v_min_u32_e32 v184, v184, v183
	v_max_u32_e32 v13, v12, v15
	v_min_u32_e32 v12, v12, v15
	v_max_u32_e32 v151, v154, v145
	v_min_u32_e32 v154, v154, v145
	v_max_u32_e32 v167, v170, v161
	v_min_u32_e32 v170, v170, v161
	v_max_u32_e32 v183, v186, v177
	v_min_u32_e32 v186, v186, v177
	v_max_u32_e32 v15, v14, v9
	v_min_u32_e32 v14, v14, v9
	v_max_u32_e32 v145, v16, v49
	v_min_u32_e32 v16, v16, v49
	v_max_u32_e32 v161, v17, v153
	v_min_u32_e32 v17, v17, v153
	v_max_u32_e32 v177, v18, v169
	v_min_u32_e32 v18, v18, v169
	v_max_u32_e32 v9, v19, v1
	v_min_u32_e32 v19, v19, v1
	v_max_u32_e32 v49, v144, v152
	v_min_u32_e32 v144, v144, v152
	v_max_u32_e32 v153, v160, v168
	v_min_u32_e32 v160, v160, v168
	v_max_u32_e32 v169, v176, v184
	v_min_u32_e32 v176, v176, v184
	v_max_u32_e32 v1, v4, v12
	v_min_u32_e32 v4, v4, v12
	v_max_u32_e32 v152, v49, v16
	v_min_u32_e32 v49, v49, v16
	v_max_u32_e32 v168, v153, v17
	v_min_u32_e32 v153, v153, v17
	v_max_u32_e32 v184, v169, v18
	v_min_u32_e32 v169, v169, v18
	v_max_u32_e32 v12, v1, v19
	v_min_u32_e32 v1, v1, v19
	v_max_u32_e32 v16, v119, v147
	v_min_u32_e32 v119, v119, v147
	v_max_u32_e32 v17, v155, v163
	v_min_u32_e32 v155, v155, v163
	v_max_u32_e32 v18, v171, v179
	v_min_u32_e32 v171, v171, v179
	v_max_u32_e32 v19, v3, v11
	v_min_u32_e32 v3, v3, v11
	v_max_u32_e32 v147, v146, v154
	v_min_u32_e32 v146, v146, v154
	v_max_u32_e32 v163, v162, v170
	v_min_u32_e32 v162, v162, v170
	v_max_u32_e32 v179, v178, v186
	v_min_u32_e32 v178, v178, v186
	v_max_u32_e32 v11, v6, v14
	v_min_u32_e32 v6, v6, v14
	v_max_u32_e32 v154, v147, v119
	v_min_u32_e32 v147, v147, v119
	v_max_u32_e32 v170, v163, v155
	v_min_u32_e32 v163, v163, v155
	v_max_u32_e32 v186, v179, v171
	v_min_u32_e32 v179, v179, v171
	v_max_u32_e32 v14, v11, v3
	v_min_u32_e32 v11, v11, v3
	v_max_u32_e32 v119, v16, v152
	v_min_u32_e32 v16, v16, v152
	v_max_u32_e32 v155, v17, v168
	v_min_u32_e32 v17, v17, v168
	v_max_u32_e32 v171, v18, v184
	v_min_u32_e32 v18, v18, v184
	v_max_u32_e32 v3, v19, v12
	v_min_u32_e32 v19, v19, v12
	v_max_u32_e32 v152, v154, v49
	v_min_u32_e32 v154, v154, v49
	v_max_u32_e32 v168, v170, v153
	v_min_u32_e32 v170, v170, v153
	v_max_u32_e32 v184, v186, v169
	v_min_u32_e32 v186, v186, v169
	v_max_u32_e32 v12, v14, v1
	v_min_u32_e32 v14, v14, v1
	v_max_u32_e32 v49, v147, v144
; DI void peer_half_topk(const bf16_t* qrow  , const bf16_t* subk  , int hi, int lane, LAS unsigned* ltop) {
;     ...
; #pragma unroll 1
;     for (int k = 0; k < 16; ++k) {
;         unsigned mx = keys[0];
; #pragma unroll
;         for (int i = 1; i < 64; ++i) mx = mx > keys[i] ? mx : keys[i];
;         const unsigned om = (unsigned)__shfl_xor((int)mx, 32);
;         mx = mx > om ? mx : om;
;         ltop[k * 64 + lane] = mx;
; #pragma unroll
;         for (int i = 0; i < 64; ++i) keys[i] = keys[i] == mx ? 0u : keys[i];
;     }
	v_min_u32_e32 v147, v147, v144
	v_max_u32_e32 v153, v163, v160
	v_min_u32_e32 v163, v163, v160
	v_max_u32_e32 v169, v179, v176
	v_min_u32_e32 v179, v179, v176
	v_max_u32_e32 v1, v11, v4
	v_min_u32_e32 v11, v11, v4
	v_max_u32_e32 v144, v142, v150
	v_min_u32_e32 v142, v142, v150
	v_max_u32_e32 v160, v158, v166
	v_min_u32_e32 v158, v158, v166
	v_max_u32_e32 v176, v174, v182
	v_min_u32_e32 v174, v174, v182
	v_max_u32_e32 v4, v2, v10
	v_min_u32_e32 v2, v2, v10
	v_max_u32_e32 v150, v143, v151
	v_min_u32_e32 v143, v143, v151
	v_max_u32_e32 v166, v159, v167
	v_min_u32_e32 v159, v159, v167
	v_max_u32_e32 v182, v175, v183
	v_min_u32_e32 v175, v175, v183
	v_max_u32_e32 v10, v7, v15
	v_min_u32_e32 v7, v7, v15
	v_max_u32_e32 v151, v150, v142
	v_min_u32_e32 v150, v150, v142
	v_max_u32_e32 v167, v166, v158
	v_min_u32_e32 v166, v166, v158
	v_max_u32_e32 v183, v182, v174
	v_min_u32_e32 v182, v182, v174
	v_max_u32_e32 v15, v10, v2
	v_min_u32_e32 v10, v10, v2
	v_max_u32_e32 v142, v131, v149
	v_min_u32_e32 v131, v131, v149
	v_max_u32_e32 v158, v157, v165
	v_min_u32_e32 v157, v157, v165
	v_max_u32_e32 v174, v173, v181
	v_min_u32_e32 v173, v173, v181
	v_max_u32_e32 v2, v5, v13
	v_min_u32_e32 v5, v5, v13
	v_max_u32_e32 v149, v128, v148
	v_min_u32_e32 v128, v128, v148
	v_max_u32_e32 v165, v156, v164
	v_min_u32_e32 v156, v156, v164
	v_max_u32_e32 v181, v172, v180
	v_min_u32_e32 v172, v172, v180
	v_max_u32_e32 v13, v0, v8
	v_min_u32_e32 v0, v0, v8
	v_max_u32_e32 v148, v149, v131
	v_min_u32_e32 v149, v149, v131
	v_max_u32_e32 v164, v165, v157
	v_min_u32_e32 v165, v165, v157
	v_max_u32_e32 v180, v181, v173
	v_min_u32_e32 v181, v181, v173
	v_max_u32_e32 v8, v13, v5
	v_min_u32_e32 v13, v13, v5
	v_max_u32_e32 v131, v142, v151
	v_min_u32_e32 v142, v142, v151
	v_max_u32_e32 v157, v158, v167
	v_min_u32_e32 v158, v158, v167
	v_max_u32_e32 v173, v174, v183
	v_min_u32_e32 v174, v174, v183
	v_max_u32_e32 v5, v2, v15
	v_min_u32_e32 v2, v2, v15
	v_max_u32_e32 v151, v148, v150
	v_min_u32_e32 v148, v148, v150
	v_max_u32_e32 v167, v164, v166
	v_min_u32_e32 v164, v164, v166
	v_max_u32_e32 v183, v180, v182
	v_min_u32_e32 v180, v180, v182
	v_max_u32_e32 v15, v8, v10
	v_min_u32_e32 v8, v8, v10
	v_max_u32_e32 v150, v149, v143
	v_min_u32_e32 v149, v149, v143
	v_max_u32_e32 v166, v165, v159
	v_min_u32_e32 v165, v165, v159
	v_max_u32_e32 v182, v181, v175
	v_min_u32_e32 v181, v181, v175
	v_max_u32_e32 v10, v13, v7
	v_min_u32_e32 v13, v13, v7
	v_max_u32_e32 v143, v144, v119
	v_min_u32_e32 v144, v144, v119
	v_max_u32_e32 v159, v160, v155
	v_min_u32_e32 v160, v160, v155
	v_max_u32_e32 v175, v176, v171
	v_min_u32_e32 v176, v176, v171
	v_max_u32_e32 v7, v4, v3
	v_min_u32_e32 v4, v4, v3
	v_max_u32_e32 v119, v131, v16
	v_min_u32_e32 v131, v131, v16
	v_max_u32_e32 v155, v157, v17
	v_min_u32_e32 v157, v157, v17
	v_max_u32_e32 v171, v173, v18
	v_min_u32_e32 v173, v173, v18
	v_max_u32_e32 v3, v5, v19
	v_min_u32_e32 v5, v5, v19
	v_max_u32_e32 v16, v142, v152
	v_min_u32_e32 v142, v142, v152
	v_max_u32_e32 v17, v158, v168
	v_min_u32_e32 v158, v158, v168
	v_max_u32_e32 v18, v174, v184
	v_min_u32_e32 v174, v174, v184
	v_max_u32_e32 v19, v2, v12
	v_min_u32_e32 v2, v2, v12
	v_max_u32_e32 v152, v151, v154
	v_min_u32_e32 v151, v151, v154
	v_max_u32_e32 v168, v167, v170
	v_min_u32_e32 v167, v167, v170
	v_max_u32_e32 v184, v183, v186
	v_min_u32_e32 v183, v183, v186
	v_max_u32_e32 v12, v15, v14
	v_min_u32_e32 v15, v15, v14
	v_max_u32_e32 v154, v148, v49
	v_min_u32_e32 v148, v148, v49
	v_max_u32_e32 v170, v164, v153
	v_min_u32_e32 v164, v164, v153
	v_max_u32_e32 v186, v180, v169
	v_min_u32_e32 v180, v180, v169
	v_max_u32_e32 v14, v8, v1
	v_min_u32_e32 v8, v8, v1
	v_max_u32_e32 v49, v150, v147
	v_min_u32_e32 v150, v150, v147
	v_max_u32_e32 v153, v166, v163
	v_min_u32_e32 v166, v166, v163
	v_max_u32_e32 v169, v182, v179
	v_min_u32_e32 v182, v182, v179
	v_max_u32_e32 v1, v10, v11
	v_min_u32_e32 v10, v10, v11
	v_max_u32_e32 v147, v149, v146
	v_min_u32_e32 v149, v149, v146
	v_max_u32_e32 v163, v165, v162
	v_min_u32_e32 v165, v165, v162
	v_max_u32_e32 v179, v181, v178
	v_min_u32_e32 v181, v181, v178
	v_max_u32_e32 v11, v13, v6
	v_min_u32_e32 v13, v13, v6
	v_max_u32_e32 v145, v145, v156
	v_max_u32_e32 v177, v177, v0
	v_max_u32_e32 v143, v143, v165
	v_max_u32_e32 v175, v175, v13
	v_max_u32_e32 v144, v144, v163
	v_max_u32_e32 v176, v176, v11
	v_max_u32_e32 v119, v119, v166
	v_max_u32_e32 v171, v171, v10
	v_max_u32_e32 v131, v131, v153
	v_max_u32_e32 v173, v173, v1
	v_max_u32_e32 v16, v16, v164
	v_max_u32_e32 v18, v18, v8
	v_max_u32_e32 v142, v142, v170
	v_max_u32_e32 v174, v174, v14
	v_max_u32_e32 v152, v152, v167
	v_max_u32_e32 v184, v184, v15
	v_max_u32_e32 v151, v151, v168
	v_max_u32_e32 v183, v183, v12
	v_max_u32_e32 v154, v154, v158
	v_max_u32_e32 v186, v186, v2
	v_max_u32_e32 v148, v148, v17
	v_max_u32_e32 v180, v180, v19
	v_max_u32_e32 v49, v49, v157
	v_max_u32_e32 v169, v169, v5
	v_max_u32_e32 v150, v150, v155
	v_max_u32_e32 v182, v182, v3
	v_max_u32_e32 v147, v147, v160
	v_max_u32_e32 v179, v179, v4
	v_max_u32_e32 v149, v149, v159
	v_max_u32_e32 v181, v181, v7
	v_max_u32_e32 v128, v128, v161
	v_max_u32_e32 v172, v172, v9
	v_max_u32_e32 v146, v145, v151
	v_min_u32_e32 v145, v145, v151
	v_max_u32_e32 v178, v177, v183
	v_min_u32_e32 v177, v177, v183
	v_max_u32_e32 v151, v143, v154
	v_min_u32_e32 v143, v143, v154
	v_max_u32_e32 v183, v175, v186
	v_min_u32_e32 v175, v175, v186
	v_max_u32_e32 v154, v144, v148
	v_min_u32_e32 v144, v144, v148
	v_max_u32_e32 v186, v176, v180
	v_min_u32_e32 v176, v176, v180
	v_max_u32_e32 v148, v119, v49
	v_min_u32_e32 v119, v119, v49
	v_max_u32_e32 v180, v171, v169
	v_min_u32_e32 v171, v171, v169
; DI void peer_half_topk(const bf16_t* qrow  , const bf16_t* subk  , int hi, int lane, LAS unsigned* ltop) {
;     ...
; #pragma unroll 1
;     for (int k = 0; k < 16; ++k) {
;         unsigned mx = keys[0];
; #pragma unroll
;         for (int i = 1; i < 64; ++i) mx = mx > keys[i] ? mx : keys[i];
;         const unsigned om = (unsigned)__shfl_xor((int)mx, 32);
;         mx = mx > om ? mx : om;
;         ltop[k * 64 + lane] = mx;
; #pragma unroll
;         for (int i = 0; i < 64; ++i) keys[i] = keys[i] == mx ? 0u : keys[i];
;     }
	v_max_u32_e32 v49, v131, v150
	v_min_u32_e32 v131, v131, v150
	v_max_u32_e32 v169, v173, v182
	v_min_u32_e32 v173, v173, v182
	v_max_u32_e32 v150, v16, v147
	v_min_u32_e32 v16, v16, v147
	v_max_u32_e32 v182, v18, v179
	v_min_u32_e32 v18, v18, v179
	v_max_u32_e32 v147, v142, v149
	v_min_u32_e32 v142, v142, v149
	v_max_u32_e32 v179, v174, v181
	v_min_u32_e32 v174, v174, v181
	v_max_u32_e32 v149, v152, v128
	v_min_u32_e32 v152, v152, v128
	v_max_u32_e32 v181, v184, v172
	v_min_u32_e32 v184, v184, v172
	v_max_u32_e32 v128, v146, v49
	v_min_u32_e32 v146, v146, v49
	v_max_u32_e32 v172, v178, v169
	v_min_u32_e32 v178, v178, v169
	v_max_u32_e32 v49, v151, v150
	v_min_u32_e32 v151, v151, v150
	v_max_u32_e32 v169, v183, v182
	v_min_u32_e32 v183, v183, v182
	v_max_u32_e32 v150, v154, v147
	v_min_u32_e32 v154, v154, v147
	v_max_u32_e32 v182, v186, v179
	v_min_u32_e32 v186, v186, v179
	v_max_u32_e32 v147, v148, v149
	v_min_u32_e32 v148, v148, v149
	v_max_u32_e32 v179, v180, v181
	v_min_u32_e32 v180, v180, v181
	v_max_u32_e32 v149, v145, v131
	v_min_u32_e32 v145, v145, v131
	v_max_u32_e32 v181, v177, v173
	v_min_u32_e32 v177, v177, v173
	v_max_u32_e32 v131, v143, v16
	v_min_u32_e32 v143, v143, v16
	v_max_u32_e32 v173, v175, v18
	v_min_u32_e32 v175, v175, v18
	v_max_u32_e32 v16, v144, v142
	v_min_u32_e32 v144, v144, v142
	v_max_u32_e32 v18, v176, v174
	v_min_u32_e32 v176, v176, v174
	v_max_u32_e32 v142, v119, v152
	v_min_u32_e32 v119, v119, v152
	v_max_u32_e32 v174, v171, v184
	v_min_u32_e32 v171, v171, v184
	v_max_u32_e32 v152, v128, v150
	v_min_u32_e32 v128, v128, v150
	v_max_u32_e32 v184, v172, v182
	v_min_u32_e32 v172, v172, v182
	v_max_u32_e32 v150, v49, v147
	v_min_u32_e32 v49, v49, v147
	v_max_u32_e32 v182, v169, v179
	v_min_u32_e32 v169, v169, v179
	v_max_u32_e32 v147, v146, v154
	v_min_u32_e32 v146, v146, v154
	v_max_u32_e32 v179, v178, v186
	v_min_u32_e32 v178, v178, v186
	v_max_u32_e32 v154, v151, v148
	v_min_u32_e32 v151, v151, v148
	v_max_u32_e32 v186, v183, v180
	v_min_u32_e32 v183, v183, v180
	v_max_u32_e32 v148, v149, v16
	v_min_u32_e32 v149, v149, v16
	v_max_u32_e32 v180, v181, v18
	v_min_u32_e32 v181, v181, v18
	v_max_u32_e32 v16, v131, v142
	v_min_u32_e32 v131, v131, v142
	v_max_u32_e32 v18, v173, v174
	v_min_u32_e32 v173, v173, v174
	v_max_u32_e32 v142, v145, v144
	v_min_u32_e32 v145, v145, v144
	v_max_u32_e32 v174, v177, v176
	v_min_u32_e32 v177, v177, v176
	v_max_u32_e32 v144, v143, v119
	v_min_u32_e32 v143, v143, v119
	v_max_u32_e32 v176, v175, v171
	v_min_u32_e32 v175, v175, v171
	v_max_u32_e32 v119, v152, v150
	v_min_u32_e32 v152, v152, v150
	v_max_u32_e32 v171, v184, v182
	v_min_u32_e32 v184, v184, v182
	v_max_u32_e32 v150, v128, v49
	v_min_u32_e32 v128, v128, v49
	v_max_u32_e32 v182, v172, v169
	v_min_u32_e32 v172, v172, v169
	v_max_u32_e32 v49, v147, v154
	v_min_u32_e32 v147, v147, v154
	v_max_u32_e32 v169, v179, v186
	v_min_u32_e32 v179, v179, v186
	v_max_u32_e32 v154, v146, v151
	v_min_u32_e32 v146, v146, v151
	v_max_u32_e32 v186, v178, v183
	v_min_u32_e32 v178, v178, v183
	v_max_u32_e32 v151, v148, v16
	v_min_u32_e32 v148, v148, v16
	v_max_u32_e32 v183, v180, v18
	v_min_u32_e32 v180, v180, v18
	v_max_u32_e32 v16, v149, v131
	v_min_u32_e32 v149, v149, v131
	v_max_u32_e32 v18, v181, v173
	v_min_u32_e32 v181, v181, v173
	v_max_u32_e32 v131, v142, v144
	v_min_u32_e32 v142, v142, v144
	v_max_u32_e32 v173, v174, v176
	v_min_u32_e32 v174, v174, v176
	v_max_u32_e32 v144, v145, v143
	v_min_u32_e32 v145, v145, v143
	v_max_u32_e32 v176, v177, v175
	v_min_u32_e32 v177, v177, v175
	v_max_u32_e32 v119, v119, v177
	v_max_u32_e32 v152, v152, v176
	v_max_u32_e32 v150, v150, v174
	v_max_u32_e32 v128, v128, v173
	v_max_u32_e32 v49, v49, v181
	v_max_u32_e32 v147, v147, v18
	v_max_u32_e32 v154, v154, v180
	v_max_u32_e32 v146, v146, v183
	v_max_u32_e32 v151, v151, v178
	v_max_u32_e32 v148, v148, v186
	v_max_u32_e32 v16, v16, v179
	v_max_u32_e32 v149, v149, v169
	v_max_u32_e32 v131, v131, v172
	v_max_u32_e32 v142, v142, v182
	v_max_u32_e32 v144, v144, v184
	v_max_u32_e32 v145, v145, v171
	v_max_u32_e32 v143, v119, v151
	v_min_u32_e32 v119, v119, v151
	v_max_u32_e32 v151, v152, v148
	v_min_u32_e32 v152, v152, v148
	v_max_u32_e32 v148, v150, v16
	v_min_u32_e32 v150, v150, v16
	v_max_u32_e32 v16, v128, v149
	v_min_u32_e32 v128, v128, v149
	v_max_u32_e32 v149, v49, v131
	v_min_u32_e32 v49, v49, v131
	v_max_u32_e32 v131, v147, v142
	v_min_u32_e32 v147, v147, v142
	v_max_u32_e32 v142, v154, v144
	v_min_u32_e32 v154, v154, v144
	v_max_u32_e32 v144, v146, v145
	v_min_u32_e32 v146, v146, v145
	v_max_u32_e32 v145, v143, v149
	v_min_u32_e32 v143, v143, v149
	v_max_u32_e32 v149, v151, v131
	v_min_u32_e32 v151, v151, v131
	v_max_u32_e32 v131, v148, v142
	v_min_u32_e32 v148, v148, v142
	v_max_u32_e32 v142, v16, v144
	v_min_u32_e32 v16, v16, v144
	v_max_u32_e32 v144, v119, v49
	v_min_u32_e32 v119, v119, v49
	v_max_u32_e32 v49, v152, v147
	v_min_u32_e32 v152, v152, v147
	v_max_u32_e32 v147, v150, v154
	v_min_u32_e32 v150, v150, v154
	v_max_u32_e32 v154, v128, v146
	v_min_u32_e32 v128, v128, v146
	v_max_u32_e32 v146, v145, v131
	v_min_u32_e32 v145, v145, v131
	v_max_u32_e32 v131, v149, v142
	v_min_u32_e32 v149, v149, v142
	v_max_u32_e32 v142, v143, v148
	v_min_u32_e32 v143, v143, v148
	v_max_u32_e32 v148, v151, v16
	v_min_u32_e32 v151, v151, v16
	v_max_u32_e32 v16, v144, v147
	v_min_u32_e32 v144, v144, v147
	v_max_u32_e32 v147, v49, v154
	v_min_u32_e32 v49, v49, v154
	v_max_u32_e32 v154, v119, v150
	v_min_u32_e32 v119, v119, v150
	v_max_u32_e32 v150, v152, v128
	v_min_u32_e32 v152, v152, v128
	v_max_u32_e32 v128, v146, v131
	v_min_u32_e32 v146, v146, v131
	v_max_u32_e32 v131, v145, v149
	v_min_u32_e32 v145, v145, v149
	v_max_u32_e32 v149, v142, v148
	v_min_u32_e32 v142, v142, v148
	v_max_u32_e32 v148, v143, v151
	v_min_u32_e32 v143, v143, v151
	v_max_u32_e32 v151, v16, v147
	v_min_u32_e32 v16, v16, v147
	v_max_u32_e32 v147, v144, v49
	v_min_u32_e32 v144, v144, v49
	v_max_u32_e32 v49, v154, v150
	v_min_u32_e32 v154, v154, v150
	v_max_u32_e32 v150, v119, v152
	v_min_u32_e32 v119, v119, v152
	ds_bpermute_b32 v156, v188, v128
	ds_bpermute_b32 v153, v188, v146
	ds_bpermute_b32 v158, v188, v131
	ds_bpermute_b32 v155, v188, v145
	ds_bpermute_b32 v160, v188, v149
	ds_bpermute_b32 v157, v188, v142
	ds_bpermute_b32 v162, v188, v148
	ds_bpermute_b32 v159, v188, v143
	ds_bpermute_b32 v164, v188, v151
	ds_bpermute_b32 v161, v188, v16
	ds_bpermute_b32 v166, v188, v147
	ds_bpermute_b32 v163, v188, v144
	ds_bpermute_b32 v168, v188, v49
	ds_bpermute_b32 v165, v188, v154
	ds_bpermute_b32 v170, v188, v150
	ds_bpermute_b32 v167, v188, v119
	s_waitcnt lgkmcnt(0)
; #define MFMA32(a, b, c) __builtin_amdgcn_mfma_f32_32x32x16_bf16((a), (b), (c), 0, 0, 0)
; DI void peer_half_topk(const bf16_t* qrow  , const bf16_t* subk  , int hi, int lane, LAS unsigned* ltop) {
;     ...
;     for (int rt = 0; rt < 4; ++rt) {
;         f32x16 acc;
; #pragma unroll
;         for (int r = 0; r < 16; ++r) acc[r] = 0.f;
; #pragma unroll
;         for (int kk = 0; kk < 8; ++kk) {
;             const bf16x8 af = *(const bf16x8*)(subk + (size_t)(rt * 32) * 128 + kk * 16);
;             const bf16x8 bf = *(const bf16x8*)(qrow + kk * 16);
;             acc = MFMA32(af, bf, acc);
;         }
;     ...
; #pragma unroll 1
;     for (int k = 0; k < 16; ++k) {
;         unsigned mx = keys[0];
; #pragma unroll
;         for (int i = 1; i < 64; ++i) mx = mx > keys[i] ? mx : keys[i];
;         const unsigned om = (unsigned)__shfl_xor((int)mx, 32);
;         mx = mx > om ? mx : om;
;         ltop[k * 64 + lane] = mx;
; #pragma unroll
;         for (int i = 0; i < 64; ++i) keys[i] = keys[i] == mx ? 0u : keys[i];
;     }
	v_max_u32_e32 v128, v128, v167
	v_max_u32_e32 v146, v146, v170
	v_max_u32_e32 v131, v131, v165
	v_max_u32_e32 v145, v145, v168
	v_max_u32_e32 v149, v149, v163
	v_max_u32_e32 v142, v142, v166
	v_max_u32_e32 v148, v148, v161
	v_max_u32_e32 v143, v143, v164
	v_max_u32_e32 v151, v151, v159
	v_max_u32_e32 v16, v16, v162
	v_max_u32_e32 v147, v147, v157
	v_max_u32_e32 v144, v144, v160
	v_max_u32_e32 v49, v49, v155
	v_max_u32_e32 v154, v154, v158
	v_max_u32_e32 v150, v150, v153
	v_max_u32_e32 v119, v119, v156
	v_max_u32_e32 v152, v128, v151
	v_min_u32_e32 v128, v128, v151
	v_max_u32_e32 v151, v146, v16
	v_min_u32_e32 v146, v146, v16
	v_max_u32_e32 v16, v131, v147
	v_min_u32_e32 v131, v131, v147
	v_max_u32_e32 v147, v145, v144
	v_min_u32_e32 v145, v145, v144
	v_max_u32_e32 v144, v149, v49
	v_min_u32_e32 v149, v149, v49
	v_max_u32_e32 v49, v142, v154
	v_min_u32_e32 v142, v142, v154
	v_max_u32_e32 v154, v148, v150
	v_min_u32_e32 v148, v148, v150
	v_max_u32_e32 v150, v143, v119
	v_min_u32_e32 v143, v143, v119
	v_max_u32_e32 v119, v152, v144
	v_min_u32_e32 v152, v152, v144
	v_max_u32_e32 v144, v151, v49
	v_min_u32_e32 v151, v151, v49
	v_max_u32_e32 v49, v16, v154
	v_min_u32_e32 v16, v16, v154
	v_max_u32_e32 v154, v147, v150
	v_min_u32_e32 v147, v147, v150
	v_max_u32_e32 v150, v128, v149
	v_min_u32_e32 v128, v128, v149
	v_max_u32_e32 v149, v146, v142
	v_min_u32_e32 v146, v146, v142
	v_max_u32_e32 v142, v131, v148
	v_min_u32_e32 v131, v131, v148
	v_max_u32_e32 v148, v145, v143
	v_min_u32_e32 v145, v145, v143
	v_max_u32_e32 v143, v119, v49
	v_min_u32_e32 v119, v119, v49
	v_max_u32_e32 v49, v144, v154
	v_min_u32_e32 v144, v144, v154
	v_max_u32_e32 v154, v152, v16
	v_min_u32_e32 v152, v152, v16
	v_max_u32_e32 v16, v151, v147
	v_min_u32_e32 v151, v151, v147
	v_max_u32_e32 v147, v150, v142
	v_min_u32_e32 v150, v150, v142
	v_max_u32_e32 v142, v149, v148
	v_min_u32_e32 v149, v149, v148
	v_max_u32_e32 v148, v128, v131
	v_min_u32_e32 v128, v128, v131
	v_max_u32_e32 v131, v146, v145
	v_min_u32_e32 v146, v146, v145
	v_max_u32_e32 v145, v143, v49
	v_min_u32_e32 v143, v143, v49
	v_max_u32_e32 v49, v119, v144
	v_min_u32_e32 v119, v119, v144
	v_max_u32_e32 v144, v154, v16
	v_min_u32_e32 v154, v154, v16
	v_max_u32_e32 v16, v152, v151
	v_min_u32_e32 v152, v152, v151
	v_max_u32_e32 v151, v147, v142
	v_min_u32_e32 v147, v147, v142
	v_max_u32_e32 v142, v150, v149
	v_min_u32_e32 v150, v150, v149
	v_max_u32_e32 v149, v148, v131
	v_min_u32_e32 v148, v148, v131
	v_max_u32_e32 v131, v128, v146
	v_min_u32_e32 v128, v128, v146
	ds_write_b32 v216, v145
	ds_write_b32 v216, v143 offset:256
	ds_write_b32 v216, v49 offset:512
	ds_write_b32 v216, v119 offset:768
	ds_write_b32 v216, v144 offset:1024
	ds_write_b32 v216, v154 offset:1280
	ds_write_b32 v216, v16 offset:1536
	ds_write_b32 v216, v152 offset:1792
	ds_write_b32 v216, v151 offset:2048
	ds_write_b32 v216, v147 offset:2304
	ds_write_b32 v216, v142 offset:2560
	ds_write_b32 v216, v150 offset:2816
	ds_write_b32 v216, v149 offset:3072
	ds_write_b32 v216, v148 offset:3328
	ds_write_b32 v216, v131 offset:3584
	ds_write_b32 v216, v128 offset:3840
	v_mov_b64_e32 v[186:187], v[120:121]
	flat_load_dwordx4 v[0:3], v[186:187]
	global_load_dwordx4 v[44:47], v[140:141], off offset:256
	flat_load_dwordx4 v[16:19], v[186:187] offset:32
	global_load_dwordx4 v[40:43], v[140:141], off offset:288
	s_mov_b32 s8, 0
	s_waitcnt vmcnt(0) lgkmcnt(0)
	v_mfma_f32_32x32x16_bf16 v[0:15], v[0:3], v[44:47], 0
	v_mfma_f32_32x32x16_bf16 v[0:15], v[16:19], v[40:43], v[0:15]
	flat_load_dwordx4 v[16:19], v[186:187] offset:64
	global_load_dwordx4 v[36:39], v[140:141], off offset:320
	s_waitcnt vmcnt(0) lgkmcnt(0)
	v_mfma_f32_32x32x16_bf16 v[0:15], v[16:19], v[36:39], v[0:15]
	flat_load_dwordx4 v[16:19], v[186:187] offset:96
	global_load_dwordx4 v[32:35], v[140:141], off offset:352
	s_waitcnt vmcnt(0) lgkmcnt(0)
	v_mfma_f32_32x32x16_bf16 v[0:15], v[16:19], v[32:35], v[0:15]
	flat_load_dwordx4 v[16:19], v[186:187] offset:128
	global_load_dwordx4 v[28:31], v[140:141], off offset:384
	s_waitcnt vmcnt(0) lgkmcnt(0)
	v_mfma_f32_32x32x16_bf16 v[0:15], v[16:19], v[28:31], v[0:15]
	flat_load_dwordx4 v[16:19], v[186:187] offset:160
	global_load_dwordx4 v[20:23], v[140:141], off offset:416
	s_waitcnt vmcnt(0) lgkmcnt(0)
	v_mfma_f32_32x32x16_bf16 v[0:15], v[16:19], v[20:23], v[0:15]
	flat_load_dwordx4 v[16:19], v[186:187] offset:192
	global_load_dwordx4 v[24:27], v[140:141], off offset:448
	s_waitcnt vmcnt(0) lgkmcnt(0)
	v_mfma_f32_32x32x16_bf16 v[0:15], v[16:19], v[24:27], v[0:15]
	flat_load_dwordx4 v[142:145], v[186:187] offset:224
	global_load_dwordx4 v[16:19], v[140:141], off offset:480
	s_waitcnt vmcnt(0) lgkmcnt(0)
; #define MFMA32(a, b, c) __builtin_amdgcn_mfma_f32_32x32x16_bf16((a), (b), (c), 0, 0, 0)
; DI int crow(int r, int hi) { return (r & 3) + 8 * (r >> 2) + 4 * hi; }
; DI unsigned ordf(float f) { const unsigned u = __builtin_bit_cast(unsigned, f); return (u & 0x80000000u) ? ~u : (u | 0x80000000u); }
; DI void peer_half_topk(const bf16_t* qrow  , const bf16_t* subk  , int hi, int lane, LAS unsigned* ltop) {
;     ...
;         for (int kk = 0; kk < 8; ++kk) {
;             const bf16x8 af = *(const bf16x8*)(subk + (size_t)(rt * 32) * 128 + kk * 16);
;             const bf16x8 bf = *(const bf16x8*)(qrow + kk * 16);
;             acc = MFMA32(af, bf, acc);
;         }
; #pragma unroll
;         for (int r = 0; r < 16; ++r) { const int n = rt * 32 + crow(r, hi); keys[rt * 16 + r] = (ordf(acc[r]) & ~0x7Fu) | (unsigned)(127 - n); }
	v_mfma_f32_32x32x16_bf16 v[0:15], v[142:145], v[16:19], v[0:15]
	s_nop 11
	v_and_b32_e32 v141, 0x7fffffff, v1
	v_and_b32_e32 v140, 0x7fffffff, v0
	v_xor_b32_e32 v49, -1, v1
	v_xor_b32_e32 v119, -1, v0
	v_pk_add_f32 v[140:141], v[140:141], 0 neg_lo:[1,1] neg_hi:[1,1]
	v_cmp_gt_i32_e32 vcc, 0, v0
	v_cmp_gt_i32_e64 s[0:1], 0, v1
	v_xor_b32_e32 v131, -1, v2
	v_cndmask_b32_e32 v1, v140, v119, vcc
	v_cndmask_b32_e64 v0, v141, v49, s[0:1]
	v_and_b32_e32 v0, 0xffffff80, v0
	v_and_b32_e32 v1, 0xffffff80, v1
	v_add_u32_e32 v49, v0, v51
	v_add_u32_e32 v128, v1, v56
	v_and_b32_e32 v1, 0x7fffffff, v3
	v_and_b32_e32 v0, 0x7fffffff, v2
	v_xor_b32_e32 v119, -1, v3
	v_pk_add_f32 v[0:1], v[0:1], 0 neg_lo:[1,1] neg_hi:[1,1]
	v_cmp_gt_i32_e32 vcc, 0, v2
	v_cmp_gt_i32_e64 s[0:1], 0, v3
	v_xor_b32_e32 v2, -1, v5
	v_cndmask_b32_e32 v0, v0, v131, vcc
	v_cndmask_b32_e64 v1, v1, v119, s[0:1]
	v_and_b32_e32 v1, 0xffffff80, v1
	v_and_b32_e32 v0, 0xffffff80, v0
	v_add_u32_e32 v119, v1, v57
	v_add_u32_e32 v140, v0, v58
	v_and_b32_e32 v1, 0x7fffffff, v5
	v_and_b32_e32 v0, 0x7fffffff, v4
	v_xor_b32_e32 v3, -1, v4
	v_pk_add_f32 v[0:1], v[0:1], 0 neg_lo:[1,1] neg_hi:[1,1]
	v_cmp_gt_i32_e32 vcc, 0, v4
	v_cmp_gt_i32_e64 s[0:1], 0, v5
	s_nop 0
	v_cndmask_b32_e32 v0, v0, v3, vcc
	v_cndmask_b32_e64 v1, v1, v2, s[0:1]
	v_and_b32_e32 v1, 0xffffff80, v1
	v_and_b32_e32 v0, 0xffffff80, v0
	v_add_u32_e32 v131, v1, v59
	v_add_u32_e32 v142, v0, v60
	v_and_b32_e32 v1, 0x7fffffff, v7
	v_and_b32_e32 v0, 0x7fffffff, v6
	v_xor_b32_e32 v2, -1, v7
	v_xor_b32_e32 v3, -1, v6
	v_pk_add_f32 v[0:1], v[0:1], 0 neg_lo:[1,1] neg_hi:[1,1]
	v_cmp_gt_i32_e32 vcc, 0, v6
	v_cmp_gt_i32_e64 s[0:1], 0, v7
	s_nop 0
	v_cndmask_b32_e32 v0, v0, v3, vcc
	v_cndmask_b32_e64 v1, v1, v2, s[0:1]
	v_and_b32_e32 v1, 0xffffff80, v1
	v_and_b32_e32 v0, 0xffffff80, v0
	v_add_u32_e32 v141, v1, v61
	v_add_u32_e32 v144, v0, v62
	v_and_b32_e32 v1, 0x7fffffff, v9
	v_and_b32_e32 v0, 0x7fffffff, v8
	v_xor_b32_e32 v2, -1, v9
	v_xor_b32_e32 v3, -1, v8
	v_pk_add_f32 v[0:1], v[0:1], 0 neg_lo:[1,1] neg_hi:[1,1]
	v_cmp_gt_i32_e32 vcc, 0, v8
	v_cmp_gt_i32_e64 s[0:1], 0, v9
	s_nop 0
	v_cndmask_b32_e32 v0, v0, v3, vcc
	v_cndmask_b32_e64 v1, v1, v2, s[0:1]
	v_and_b32_e32 v1, 0xffffff80, v1
	v_and_b32_e32 v0, 0xffffff80, v0
	v_add_u32_e32 v143, v1, v63
	v_add_u32_e32 v146, v0, v64
	v_and_b32_e32 v1, 0x7fffffff, v11
	v_and_b32_e32 v0, 0x7fffffff, v10
	v_xor_b32_e32 v2, -1, v11
	v_xor_b32_e32 v3, -1, v10
	v_pk_add_f32 v[0:1], v[0:1], 0 neg_lo:[1,1] neg_hi:[1,1]
	v_cmp_gt_i32_e32 vcc, 0, v10
	v_cmp_gt_i32_e64 s[0:1], 0, v11
	s_nop 0
	v_cndmask_b32_e32 v0, v0, v3, vcc
	v_cndmask_b32_e64 v1, v1, v2, s[0:1]
	v_and_b32_e32 v1, 0xffffff80, v1
	v_and_b32_e32 v0, 0xffffff80, v0
	v_add_u32_e32 v145, v1, v65
	v_add_u32_e32 v148, v0, v66
	v_and_b32_e32 v1, 0x7fffffff, v13
	v_and_b32_e32 v0, 0x7fffffff, v12
	v_xor_b32_e32 v2, -1, v13
	v_xor_b32_e32 v3, -1, v12
	v_pk_add_f32 v[0:1], v[0:1], 0 neg_lo:[1,1] neg_hi:[1,1]
	v_cmp_gt_i32_e32 vcc, 0, v12
	v_cmp_gt_i32_e64 s[0:1], 0, v13
	s_nop 0
	v_cndmask_b32_e32 v0, v0, v3, vcc
	v_cndmask_b32_e64 v1, v1, v2, s[0:1]
	v_and_b32_e32 v1, 0xffffff80, v1
	v_and_b32_e32 v0, 0xffffff80, v0
	v_add_u32_e32 v147, v1, v67
	v_add_u32_e32 v150, v0, v68
	v_and_b32_e32 v1, 0x7fffffff, v15
	v_and_b32_e32 v0, 0x7fffffff, v14
	v_xor_b32_e32 v2, -1, v15
	v_pk_add_f32 v[0:1], v[0:1], 0 neg_lo:[1,1] neg_hi:[1,1]
	v_cmp_gt_i32_e64 s[0:1], 0, v15
	v_xor_b32_e32 v3, -1, v14
	v_cmp_gt_i32_e32 vcc, 0, v14
	v_cndmask_b32_e64 v1, v1, v2, s[0:1]
	s_movk_i32 s0, 0x2000
	v_cndmask_b32_e32 v0, v0, v3, vcc
	v_add_co_u32_e32 v158, vcc, s0, v186
	v_and_b32_e32 v1, 0xffffff80, v1
	v_and_b32_e32 v0, 0xffffff80, v0
	v_addc_co_u32_e32 v159, vcc, 0, v187, vcc
	v_add_u32_e32 v149, v1, v69
	v_add_u32_e32 v152, v0, v70
	flat_load_dwordx4 v[0:3], v[158:159]
	flat_load_dwordx4 v[154:157], v[158:159] offset:32
	s_waitcnt vmcnt(0) lgkmcnt(0)
	v_mfma_f32_32x32x16_bf16 v[0:15], v[0:3], v[44:47], 0
	v_mfma_f32_32x32x16_bf16 v[0:15], v[154:157], v[40:43], v[0:15]
	flat_load_dwordx4 v[154:157], v[158:159] offset:64
	s_waitcnt vmcnt(0) lgkmcnt(0)
	v_mfma_f32_32x32x16_bf16 v[0:15], v[154:157], v[36:39], v[0:15]
	flat_load_dwordx4 v[154:157], v[158:159] offset:96
	s_waitcnt vmcnt(0) lgkmcnt(0)
	v_mfma_f32_32x32x16_bf16 v[0:15], v[154:157], v[32:35], v[0:15]
	flat_load_dwordx4 v[154:157], v[158:159] offset:128
	s_waitcnt vmcnt(0) lgkmcnt(0)
	v_mfma_f32_32x32x16_bf16 v[0:15], v[154:157], v[28:31], v[0:15]
	flat_load_dwordx4 v[154:157], v[158:159] offset:160
	s_waitcnt vmcnt(0) lgkmcnt(0)
	v_mfma_f32_32x32x16_bf16 v[0:15], v[154:157], v[20:23], v[0:15]
	flat_load_dwordx4 v[154:157], v[158:159] offset:192
	s_waitcnt vmcnt(0) lgkmcnt(0)
	v_mfma_f32_32x32x16_bf16 v[0:15], v[154:157], v[24:27], v[0:15]
	flat_load_dwordx4 v[154:157], v[158:159] offset:224
	s_waitcnt vmcnt(0) lgkmcnt(0)
; #define MFMA32(a, b, c) __builtin_amdgcn_mfma_f32_32x32x16_bf16((a), (b), (c), 0, 0, 0)
; DI int crow(int r, int hi) { return (r & 3) + 8 * (r >> 2) + 4 * hi; }
; DI unsigned ordf(float f) { const unsigned u = __builtin_bit_cast(unsigned, f); return (u & 0x80000000u) ? ~u : (u | 0x80000000u); }
; DI void peer_half_topk(const bf16_t* qrow  , const bf16_t* subk  , int hi, int lane, LAS unsigned* ltop) {
;     ...
;         for (int kk = 0; kk < 8; ++kk) {
;             const bf16x8 af = *(const bf16x8*)(subk + (size_t)(rt * 32) * 128 + kk * 16);
;             const bf16x8 bf = *(const bf16x8*)(qrow + kk * 16);
;             acc = MFMA32(af, bf, acc);
;         }
; #pragma unroll
;         for (int r = 0; r < 16; ++r) { const int n = rt * 32 + crow(r, hi); keys[rt * 16 + r] = (ordf(acc[r]) & ~0x7Fu) | (unsigned)(127 - n); }
	v_mfma_f32_32x32x16_bf16 v[0:15], v[154:157], v[16:19], v[0:15]
	s_nop 11
	v_and_b32_e32 v155, 0x7fffffff, v1
	v_and_b32_e32 v154, 0x7fffffff, v0
	v_xor_b32_e32 v151, -1, v1
	v_xor_b32_e32 v153, -1, v0
	v_pk_add_f32 v[154:155], v[154:155], 0 neg_lo:[1,1] neg_hi:[1,1]
	v_cmp_gt_i32_e32 vcc, 0, v0
	v_cmp_gt_i32_e64 s[0:1], 0, v1
	s_nop 0
	v_cndmask_b32_e32 v1, v154, v153, vcc
	v_cndmask_b32_e64 v0, v155, v151, s[0:1]
	v_and_b32_e32 v0, 0xffffff80, v0
	v_and_b32_e32 v1, 0xffffff80, v1
	v_add_u32_e32 v151, v0, v71
	v_add_u32_e32 v154, v1, v72
	v_and_b32_e32 v1, 0x7fffffff, v3
	v_and_b32_e32 v0, 0x7fffffff, v2
	v_xor_b32_e32 v153, -1, v3
	v_xor_b32_e32 v155, -1, v2
	v_pk_add_f32 v[0:1], v[0:1], 0 neg_lo:[1,1] neg_hi:[1,1]
	v_cmp_gt_i32_e32 vcc, 0, v2
	v_cmp_gt_i32_e64 s[0:1], 0, v3
	v_xor_b32_e32 v2, -1, v5
	v_cndmask_b32_e32 v0, v0, v155, vcc
	v_cndmask_b32_e64 v1, v1, v153, s[0:1]
	v_and_b32_e32 v1, 0xffffff80, v1
	v_and_b32_e32 v0, 0xffffff80, v0
	v_add_u32_e32 v153, v1, v73
	v_add_u32_e32 v156, v0, v74
	v_and_b32_e32 v1, 0x7fffffff, v5
	v_and_b32_e32 v0, 0x7fffffff, v4
	v_xor_b32_e32 v3, -1, v4
	v_pk_add_f32 v[0:1], v[0:1], 0 neg_lo:[1,1] neg_hi:[1,1]
	v_cmp_gt_i32_e32 vcc, 0, v4
	v_cmp_gt_i32_e64 s[0:1], 0, v5
	s_nop 0
	v_cndmask_b32_e32 v0, v0, v3, vcc
	v_cndmask_b32_e64 v1, v1, v2, s[0:1]
	v_and_b32_e32 v1, 0xffffff80, v1
	v_and_b32_e32 v0, 0xffffff80, v0
	v_add_u32_e32 v155, v1, v75
	v_add_u32_e32 v158, v0, v76
	v_and_b32_e32 v1, 0x7fffffff, v7
	v_and_b32_e32 v0, 0x7fffffff, v6
	v_xor_b32_e32 v2, -1, v7
	v_xor_b32_e32 v3, -1, v6
	v_pk_add_f32 v[0:1], v[0:1], 0 neg_lo:[1,1] neg_hi:[1,1]
	v_cmp_gt_i32_e32 vcc, 0, v6
	v_cmp_gt_i32_e64 s[0:1], 0, v7
	s_nop 0
	v_cndmask_b32_e32 v0, v0, v3, vcc
	v_cndmask_b32_e64 v1, v1, v2, s[0:1]
	v_and_b32_e32 v1, 0xffffff80, v1
	v_and_b32_e32 v0, 0xffffff80, v0
	v_add_u32_e32 v157, v1, v77
	v_add_u32_e32 v160, v0, v78
	v_and_b32_e32 v1, 0x7fffffff, v9
	v_and_b32_e32 v0, 0x7fffffff, v8
	v_xor_b32_e32 v2, -1, v9
	v_xor_b32_e32 v3, -1, v8
	v_pk_add_f32 v[0:1], v[0:1], 0 neg_lo:[1,1] neg_hi:[1,1]
	v_cmp_gt_i32_e32 vcc, 0, v8
	v_cmp_gt_i32_e64 s[0:1], 0, v9
	s_nop 0
	v_cndmask_b32_e32 v0, v0, v3, vcc
	v_cndmask_b32_e64 v1, v1, v2, s[0:1]
	v_and_b32_e32 v1, 0xffffff80, v1
	v_and_b32_e32 v0, 0xffffff80, v0
	v_add_u32_e32 v159, v1, v79
	v_add_u32_e32 v162, v0, v80
	v_and_b32_e32 v1, 0x7fffffff, v11
	v_and_b32_e32 v0, 0x7fffffff, v10
	v_xor_b32_e32 v2, -1, v11
	v_xor_b32_e32 v3, -1, v10
	v_pk_add_f32 v[0:1], v[0:1], 0 neg_lo:[1,1] neg_hi:[1,1]
	v_cmp_gt_i32_e32 vcc, 0, v10
	v_cmp_gt_i32_e64 s[0:1], 0, v11
	s_nop 0
	v_cndmask_b32_e32 v0, v0, v3, vcc
	v_cndmask_b32_e64 v1, v1, v2, s[0:1]
	v_and_b32_e32 v1, 0xffffff80, v1
	v_and_b32_e32 v0, 0xffffff80, v0
	v_add_u32_e32 v161, v1, v81
	v_add_u32_e32 v164, v0, v82
	v_and_b32_e32 v1, 0x7fffffff, v13
	v_and_b32_e32 v0, 0x7fffffff, v12
	v_xor_b32_e32 v2, -1, v13
	v_xor_b32_e32 v3, -1, v12
	v_pk_add_f32 v[0:1], v[0:1], 0 neg_lo:[1,1] neg_hi:[1,1]
	v_cmp_gt_i32_e32 vcc, 0, v12
	v_cmp_gt_i32_e64 s[0:1], 0, v13
	s_nop 0
	v_cndmask_b32_e32 v0, v0, v3, vcc
	v_cndmask_b32_e64 v1, v1, v2, s[0:1]
	v_and_b32_e32 v1, 0xffffff80, v1
	v_and_b32_e32 v0, 0xffffff80, v0
	v_add_u32_e32 v163, v1, v83
	v_add_u32_e32 v166, v0, v84
	v_and_b32_e32 v1, 0x7fffffff, v15
	v_and_b32_e32 v0, 0x7fffffff, v14
	v_xor_b32_e32 v2, -1, v15
	v_pk_add_f32 v[0:1], v[0:1], 0 neg_lo:[1,1] neg_hi:[1,1]
	v_cmp_gt_i32_e64 s[0:1], 0, v15
	v_xor_b32_e32 v3, -1, v14
	v_cmp_gt_i32_e32 vcc, 0, v14
	v_cndmask_b32_e64 v1, v1, v2, s[0:1]
	s_movk_i32 s0, 0x4000
	v_cndmask_b32_e32 v0, v0, v3, vcc
	v_add_co_u32_e32 v174, vcc, s0, v186
	v_and_b32_e32 v1, 0xffffff80, v1
	v_and_b32_e32 v0, 0xffffff80, v0
	v_addc_co_u32_e32 v175, vcc, 0, v187, vcc
	v_add_u32_e32 v165, v1, v85
	v_add_u32_e32 v168, v0, v86
	flat_load_dwordx4 v[0:3], v[174:175]
	flat_load_dwordx4 v[170:173], v[174:175] offset:32
	s_waitcnt vmcnt(0) lgkmcnt(0)
	v_mfma_f32_32x32x16_bf16 v[0:15], v[0:3], v[44:47], 0
	v_mfma_f32_32x32x16_bf16 v[0:15], v[170:173], v[40:43], v[0:15]
	flat_load_dwordx4 v[170:173], v[174:175] offset:64
	s_waitcnt vmcnt(0) lgkmcnt(0)
	v_mfma_f32_32x32x16_bf16 v[0:15], v[170:173], v[36:39], v[0:15]
	flat_load_dwordx4 v[170:173], v[174:175] offset:96
	s_waitcnt vmcnt(0) lgkmcnt(0)
	v_mfma_f32_32x32x16_bf16 v[0:15], v[170:173], v[32:35], v[0:15]
	flat_load_dwordx4 v[170:173], v[174:175] offset:128
	s_waitcnt vmcnt(0) lgkmcnt(0)
	v_mfma_f32_32x32x16_bf16 v[0:15], v[170:173], v[28:31], v[0:15]
	flat_load_dwordx4 v[170:173], v[174:175] offset:160
	s_waitcnt vmcnt(0) lgkmcnt(0)
	v_mfma_f32_32x32x16_bf16 v[0:15], v[170:173], v[20:23], v[0:15]
	flat_load_dwordx4 v[170:173], v[174:175] offset:192
	s_waitcnt vmcnt(0) lgkmcnt(0)
	v_mfma_f32_32x32x16_bf16 v[0:15], v[170:173], v[24:27], v[0:15]
	flat_load_dwordx4 v[170:173], v[174:175] offset:224
	s_waitcnt vmcnt(0) lgkmcnt(0)
; #define MFMA32(a, b, c) __builtin_amdgcn_mfma_f32_32x32x16_bf16((a), (b), (c), 0, 0, 0)
; DI int crow(int r, int hi) { return (r & 3) + 8 * (r >> 2) + 4 * hi; }
; DI unsigned ordf(float f) { const unsigned u = __builtin_bit_cast(unsigned, f); return (u & 0x80000000u) ? ~u : (u | 0x80000000u); }
; DI void peer_half_topk(const bf16_t* qrow  , const bf16_t* subk  , int hi, int lane, LAS unsigned* ltop) {
;     ...
;         for (int kk = 0; kk < 8; ++kk) {
;             const bf16x8 af = *(const bf16x8*)(subk + (size_t)(rt * 32) * 128 + kk * 16);
;             const bf16x8 bf = *(const bf16x8*)(qrow + kk * 16);
;             acc = MFMA32(af, bf, acc);
;         }
; #pragma unroll
;         for (int r = 0; r < 16; ++r) { const int n = rt * 32 + crow(r, hi); keys[rt * 16 + r] = (ordf(acc[r]) & ~0x7Fu) | (unsigned)(127 - n); }
	v_mfma_f32_32x32x16_bf16 v[0:15], v[170:173], v[16:19], v[0:15]
	s_nop 11
	v_and_b32_e32 v171, 0x7fffffff, v1
	v_and_b32_e32 v170, 0x7fffffff, v0
	v_xor_b32_e32 v167, -1, v1
	v_xor_b32_e32 v169, -1, v0
	v_pk_add_f32 v[170:171], v[170:171], 0 neg_lo:[1,1] neg_hi:[1,1]
	v_cmp_gt_i32_e32 vcc, 0, v0
	v_cmp_gt_i32_e64 s[0:1], 0, v1
	s_nop 0
	v_cndmask_b32_e32 v1, v170, v169, vcc
	v_cndmask_b32_e64 v0, v171, v167, s[0:1]
	v_and_b32_e32 v0, 0xffffff80, v0
	v_and_b32_e32 v1, 0xffffff80, v1
	v_add_u32_e32 v167, v0, v87
	v_add_u32_e32 v170, v1, v88
	v_and_b32_e32 v1, 0x7fffffff, v3
	v_and_b32_e32 v0, 0x7fffffff, v2
	v_xor_b32_e32 v169, -1, v3
	v_xor_b32_e32 v171, -1, v2
	v_pk_add_f32 v[0:1], v[0:1], 0 neg_lo:[1,1] neg_hi:[1,1]
	v_cmp_gt_i32_e32 vcc, 0, v2
	v_cmp_gt_i32_e64 s[0:1], 0, v3
	v_xor_b32_e32 v2, -1, v5
	v_cndmask_b32_e32 v0, v0, v171, vcc
	v_cndmask_b32_e64 v1, v1, v169, s[0:1]
	v_and_b32_e32 v1, 0xffffff80, v1
	v_and_b32_e32 v0, 0xffffff80, v0
	v_add_u32_e32 v169, v1, v89
	v_add_u32_e32 v172, v0, v90
	v_and_b32_e32 v1, 0x7fffffff, v5
	v_and_b32_e32 v0, 0x7fffffff, v4
	v_xor_b32_e32 v3, -1, v4
	v_pk_add_f32 v[0:1], v[0:1], 0 neg_lo:[1,1] neg_hi:[1,1]
	v_cmp_gt_i32_e32 vcc, 0, v4
	v_cmp_gt_i32_e64 s[0:1], 0, v5
	s_nop 0
	v_cndmask_b32_e32 v0, v0, v3, vcc
	v_cndmask_b32_e64 v1, v1, v2, s[0:1]
	v_and_b32_e32 v1, 0xffffff80, v1
	v_and_b32_e32 v0, 0xffffff80, v0
	v_add_u32_e32 v171, v1, v91
	v_add_u32_e32 v174, v0, v92
	v_and_b32_e32 v1, 0x7fffffff, v7
	v_and_b32_e32 v0, 0x7fffffff, v6
	v_xor_b32_e32 v2, -1, v7
	v_xor_b32_e32 v3, -1, v6
	v_pk_add_f32 v[0:1], v[0:1], 0 neg_lo:[1,1] neg_hi:[1,1]
	v_cmp_gt_i32_e32 vcc, 0, v6
	v_cmp_gt_i32_e64 s[0:1], 0, v7
	s_nop 0
	v_cndmask_b32_e32 v0, v0, v3, vcc
	v_cndmask_b32_e64 v1, v1, v2, s[0:1]
	v_and_b32_e32 v1, 0xffffff80, v1
	v_and_b32_e32 v0, 0xffffff80, v0
	v_add_u32_e32 v173, v1, v93
	v_add_u32_e32 v176, v0, v94
	v_and_b32_e32 v1, 0x7fffffff, v9
	v_and_b32_e32 v0, 0x7fffffff, v8
	v_xor_b32_e32 v2, -1, v9
	v_xor_b32_e32 v3, -1, v8
	v_pk_add_f32 v[0:1], v[0:1], 0 neg_lo:[1,1] neg_hi:[1,1]
	v_cmp_gt_i32_e32 vcc, 0, v8
	v_cmp_gt_i32_e64 s[0:1], 0, v9
	s_nop 0
	v_cndmask_b32_e32 v0, v0, v3, vcc
	v_cndmask_b32_e64 v1, v1, v2, s[0:1]
	v_and_b32_e32 v1, 0xffffff80, v1
	v_and_b32_e32 v0, 0xffffff80, v0
	v_add_u32_e32 v175, v1, v95
	v_add_u32_e32 v178, v0, v96
	v_and_b32_e32 v1, 0x7fffffff, v11
	v_and_b32_e32 v0, 0x7fffffff, v10
	v_xor_b32_e32 v2, -1, v11
	v_xor_b32_e32 v3, -1, v10
	v_pk_add_f32 v[0:1], v[0:1], 0 neg_lo:[1,1] neg_hi:[1,1]
	v_cmp_gt_i32_e32 vcc, 0, v10
	v_cmp_gt_i32_e64 s[0:1], 0, v11
	s_nop 0
	v_cndmask_b32_e32 v0, v0, v3, vcc
	v_cndmask_b32_e64 v1, v1, v2, s[0:1]
	v_and_b32_e32 v1, 0xffffff80, v1
	v_and_b32_e32 v0, 0xffffff80, v0
	v_add_u32_e32 v177, v1, v97
	v_add_u32_e32 v180, v0, v98
	v_and_b32_e32 v1, 0x7fffffff, v13
	v_and_b32_e32 v0, 0x7fffffff, v12
	v_xor_b32_e32 v2, -1, v13
	v_xor_b32_e32 v3, -1, v12
	v_pk_add_f32 v[0:1], v[0:1], 0 neg_lo:[1,1] neg_hi:[1,1]
	v_cmp_gt_i32_e32 vcc, 0, v12
	v_cmp_gt_i32_e64 s[0:1], 0, v13
	s_nop 0
	v_cndmask_b32_e32 v0, v0, v3, vcc
	v_cndmask_b32_e64 v1, v1, v2, s[0:1]
	v_and_b32_e32 v1, 0xffffff80, v1
	v_and_b32_e32 v0, 0xffffff80, v0
	v_add_u32_e32 v179, v1, v99
	v_add_u32_e32 v182, v0, v100
	v_and_b32_e32 v1, 0x7fffffff, v15
	v_and_b32_e32 v0, 0x7fffffff, v14
	v_xor_b32_e32 v2, -1, v15
	v_pk_add_f32 v[0:1], v[0:1], 0 neg_lo:[1,1] neg_hi:[1,1]
	v_cmp_gt_i32_e64 s[0:1], 0, v15
	v_xor_b32_e32 v3, -1, v14
	v_cmp_gt_i32_e32 vcc, 0, v14
	v_cndmask_b32_e64 v1, v1, v2, s[0:1]
	s_movk_i32 s0, 0x6000
	v_cndmask_b32_e32 v0, v0, v3, vcc
	v_add_co_u32_e32 v186, vcc, s0, v186
	v_and_b32_e32 v1, 0xffffff80, v1
	v_and_b32_e32 v0, 0xffffff80, v0
	v_addc_co_u32_e32 v187, vcc, 0, v187, vcc
	v_add_u32_e32 v181, v1, v101
	v_add_u32_e32 v184, v0, v102
	flat_load_dwordx4 v[0:3], v[186:187]
	s_waitcnt vmcnt(0) lgkmcnt(0)
	v_mfma_f32_32x32x16_bf16 v[0:15], v[0:3], v[44:47], 0
	flat_load_dwordx4 v[44:47], v[186:187] offset:32
	s_waitcnt vmcnt(0) lgkmcnt(0)
	v_mfma_f32_32x32x16_bf16 v[0:15], v[44:47], v[40:43], v[0:15]
	flat_load_dwordx4 v[40:43], v[186:187] offset:64
	s_waitcnt vmcnt(0) lgkmcnt(0)
	v_mfma_f32_32x32x16_bf16 v[0:15], v[40:43], v[36:39], v[0:15]
	flat_load_dwordx4 v[36:39], v[186:187] offset:96
	s_waitcnt vmcnt(0) lgkmcnt(0)
	v_mfma_f32_32x32x16_bf16 v[0:15], v[36:39], v[32:35], v[0:15]
	flat_load_dwordx4 v[32:35], v[186:187] offset:128
	s_waitcnt vmcnt(0) lgkmcnt(0)
	v_mfma_f32_32x32x16_bf16 v[0:15], v[32:35], v[28:31], v[0:15]
	flat_load_dwordx4 v[28:31], v[186:187] offset:160
	s_waitcnt vmcnt(0) lgkmcnt(0)
	v_mfma_f32_32x32x16_bf16 v[0:15], v[28:31], v[20:23], v[0:15]
	flat_load_dwordx4 v[20:23], v[186:187] offset:192
	s_waitcnt vmcnt(0) lgkmcnt(0)
	v_mfma_f32_32x32x16_bf16 v[0:15], v[20:23], v[24:27], v[0:15]
	flat_load_dwordx4 v[20:23], v[186:187] offset:224
	s_waitcnt vmcnt(0) lgkmcnt(0)
; DI int crow(int r, int hi) { return (r & 3) + 8 * (r >> 2) + 4 * hi; }
; DI unsigned ordf(float f) { const unsigned u = __builtin_bit_cast(unsigned, f); return (u & 0x80000000u) ? ~u : (u | 0x80000000u); }
; DI void peer_half_topk(const bf16_t* qrow  , const bf16_t* subk  , int hi, int lane, LAS unsigned* ltop) {
;     ...
; #pragma unroll
;         for (int r = 0; r < 16; ++r) { const int n = rt * 32 + crow(r, hi); keys[rt * 16 + r] = (ordf(acc[r]) & ~0x7Fu) | (unsigned)(127 - n); }
;     }
; #pragma unroll 1
;     for (int k = 0; k < 16; ++k) {
;         unsigned mx = keys[0];
; #pragma unroll
;         for (int i = 1; i < 64; ++i) mx = mx > keys[i] ? mx : keys[i];
;         const unsigned om = (unsigned)__shfl_xor((int)mx, 32);
;         mx = mx > om ? mx : om;
;         ltop[k * 64 + lane] = mx;
; #pragma unroll
;         for (int i = 0; i < 64; ++i) keys[i] = keys[i] == mx ? 0u : keys[i];
;     }
	v_mfma_f32_32x32x16_bf16 v[0:15], v[20:23], v[16:19], v[0:15]
	s_nop 11
	v_and_b32_e32 v17, 0x7fffffff, v1
	v_and_b32_e32 v16, 0x7fffffff, v0
	v_xor_b32_e32 v18, -1, v1
	v_xor_b32_e32 v19, -1, v0
	v_pk_add_f32 v[16:17], v[16:17], 0 neg_lo:[1,1] neg_hi:[1,1]
	v_cmp_gt_i32_e32 vcc, 0, v0
	v_cmp_gt_i32_e64 s[0:1], 0, v1
	v_cmp_gt_i32_e64 s[40:41], 0, v15
	v_cndmask_b32_e32 v1, v16, v19, vcc
	v_cndmask_b32_e64 v0, v17, v18, s[0:1]
	v_and_b32_e32 v0, 0xffffff80, v0
	v_and_b32_e32 v16, 0xffffff80, v1
	v_add_u32_e32 v1, v0, v103
	v_add_u32_e32 v0, v16, v104
	v_and_b32_e32 v17, 0x7fffffff, v3
	v_and_b32_e32 v16, 0x7fffffff, v2
	v_xor_b32_e32 v18, -1, v3
	v_xor_b32_e32 v19, -1, v2
	v_pk_add_f32 v[16:17], v[16:17], 0 neg_lo:[1,1] neg_hi:[1,1]
	v_cmp_gt_i32_e32 vcc, 0, v2
	v_cmp_gt_i32_e64 s[0:1], 0, v3
	s_nop 0
	v_cndmask_b32_e32 v3, v16, v19, vcc
	v_cndmask_b32_e64 v2, v17, v18, s[0:1]
	v_and_b32_e32 v2, 0xffffff80, v2
	v_and_b32_e32 v16, 0xffffff80, v3
	v_add_u32_e32 v3, v2, v105
	v_add_u32_e32 v2, v16, v106
	v_and_b32_e32 v17, 0x7fffffff, v5
	v_and_b32_e32 v16, 0x7fffffff, v4
	v_xor_b32_e32 v18, -1, v5
	v_xor_b32_e32 v19, -1, v4
	v_pk_add_f32 v[16:17], v[16:17], 0 neg_lo:[1,1] neg_hi:[1,1]
	v_cmp_gt_i32_e32 vcc, 0, v4
	v_cmp_gt_i32_e64 s[0:1], 0, v5
	s_nop 0
	v_cndmask_b32_e32 v5, v16, v19, vcc
	v_cndmask_b32_e64 v4, v17, v18, s[0:1]
	v_and_b32_e32 v4, 0xffffff80, v4
	v_and_b32_e32 v16, 0xffffff80, v5
	v_add_u32_e32 v5, v4, v107
	v_add_u32_e32 v4, v16, v108
	v_and_b32_e32 v17, 0x7fffffff, v7
	v_and_b32_e32 v16, 0x7fffffff, v6
	v_xor_b32_e32 v18, -1, v7
	v_xor_b32_e32 v19, -1, v6
	v_pk_add_f32 v[16:17], v[16:17], 0 neg_lo:[1,1] neg_hi:[1,1]
	v_cmp_gt_i32_e32 vcc, 0, v6
	v_cmp_gt_i32_e64 s[0:1], 0, v7
	s_nop 0
	v_cndmask_b32_e32 v7, v16, v19, vcc
	v_cndmask_b32_e64 v6, v17, v18, s[0:1]
	v_and_b32_e32 v6, 0xffffff80, v6
	v_and_b32_e32 v16, 0xffffff80, v7
	v_add_u32_e32 v7, v6, v109
	v_add_u32_e32 v6, v16, v110
	v_and_b32_e32 v17, 0x7fffffff, v9
	v_and_b32_e32 v16, 0x7fffffff, v8
	v_xor_b32_e32 v18, -1, v9
	v_xor_b32_e32 v19, -1, v8
	v_pk_add_f32 v[16:17], v[16:17], 0 neg_lo:[1,1] neg_hi:[1,1]
	v_cmp_gt_i32_e32 vcc, 0, v8
	v_cmp_gt_i32_e64 s[0:1], 0, v9
	s_nop 0
	v_cndmask_b32_e32 v9, v16, v19, vcc
	v_cndmask_b32_e64 v8, v17, v18, s[0:1]
	v_and_b32_e32 v8, 0xffffff80, v8
	v_and_b32_e32 v16, 0xffffff80, v9
	v_add_u32_e32 v9, v8, v111
	v_add_u32_e32 v8, v16, v112
	v_and_b32_e32 v17, 0x7fffffff, v11
	v_and_b32_e32 v16, 0x7fffffff, v10
	v_xor_b32_e32 v18, -1, v11
	v_xor_b32_e32 v19, -1, v10
	v_pk_add_f32 v[16:17], v[16:17], 0 neg_lo:[1,1] neg_hi:[1,1]
	v_cmp_gt_i32_e32 vcc, 0, v10
	v_cmp_gt_i32_e64 s[0:1], 0, v11
	s_nop 0
	v_cndmask_b32_e32 v11, v16, v19, vcc
	v_cndmask_b32_e64 v10, v17, v18, s[0:1]
	v_and_b32_e32 v10, 0xffffff80, v10
	v_and_b32_e32 v16, 0xffffff80, v11
	v_add_u32_e32 v11, v10, v113
	v_add_u32_e32 v10, v16, v114
	v_and_b32_e32 v17, 0x7fffffff, v13
	v_and_b32_e32 v16, 0x7fffffff, v12
	v_xor_b32_e32 v18, -1, v13
	v_xor_b32_e32 v19, -1, v12
	v_pk_add_f32 v[16:17], v[16:17], 0 neg_lo:[1,1] neg_hi:[1,1]
	v_cmp_gt_i32_e32 vcc, 0, v12
	v_cmp_gt_i32_e64 s[0:1], 0, v13
	s_nop 0
	v_cndmask_b32_e32 v13, v16, v19, vcc
	v_cndmask_b32_e64 v12, v17, v18, s[0:1]
	v_and_b32_e32 v12, 0xffffff80, v12
	v_and_b32_e32 v16, 0xffffff80, v13
	v_add_u32_e32 v13, v12, v115
	v_add_u32_e32 v12, v16, v116
	v_and_b32_e32 v17, 0x7fffffff, v15
	v_and_b32_e32 v16, 0x7fffffff, v14
	v_xor_b32_e32 v18, -1, v15
	v_xor_b32_e32 v19, -1, v14
	v_pk_add_f32 v[16:17], v[16:17], 0 neg_lo:[1,1] neg_hi:[1,1]
	v_cmp_gt_i32_e32 vcc, 0, v14
	v_cndmask_b32_e64 v14, v17, v18, s[40:41]
	v_and_b32_e32 v14, 0xffffff80, v14
	v_cndmask_b32_e32 v15, v16, v19, vcc
	v_and_b32_e32 v16, 0xffffff80, v15
	v_add_u32_e32 v15, v14, v117
	v_add_u32_e32 v14, v16, v118
.LBB0_43:
	v_max_u32_e32 v16, v128, v49
	v_min_u32_e32 v128, v128, v49
	v_max_u32_e32 v17, v154, v151
	v_min_u32_e32 v154, v154, v151
	v_max_u32_e32 v18, v170, v167
	v_min_u32_e32 v170, v170, v167
	v_max_u32_e32 v19, v0, v1
	v_min_u32_e32 v0, v0, v1
	v_max_u32_e32 v49, v140, v119
	v_min_u32_e32 v140, v140, v119
	v_max_u32_e32 v151, v156, v153
	v_min_u32_e32 v156, v156, v153
	v_max_u32_e32 v167, v172, v169
	v_min_u32_e32 v172, v172, v169
	v_max_u32_e32 v1, v2, v3
	v_min_u32_e32 v2, v2, v3
	v_max_u32_e32 v119, v16, v49
	v_min_u32_e32 v16, v16, v49
	v_max_u32_e32 v153, v17, v151
	v_min_u32_e32 v17, v17, v151
	v_max_u32_e32 v169, v18, v167
	v_min_u32_e32 v18, v18, v167
	v_max_u32_e32 v3, v19, v1
	v_min_u32_e32 v19, v19, v1
	v_max_u32_e32 v49, v128, v140
	v_min_u32_e32 v128, v128, v140
	v_max_u32_e32 v151, v154, v156
	v_min_u32_e32 v154, v154, v156
	v_max_u32_e32 v167, v170, v172
	v_min_u32_e32 v170, v170, v172
	v_max_u32_e32 v1, v0, v2
	v_min_u32_e32 v0, v0, v2
	v_max_u32_e32 v140, v49, v16
	v_min_u32_e32 v49, v49, v16
	v_max_u32_e32 v156, v151, v17
	v_min_u32_e32 v151, v151, v17
	v_max_u32_e32 v172, v167, v18
	v_min_u32_e32 v167, v167, v18
	v_max_u32_e32 v2, v1, v19
	v_min_u32_e32 v1, v1, v19
	v_max_u32_e32 v16, v142, v131
	v_min_u32_e32 v142, v142, v131
	v_max_u32_e32 v17, v158, v155
	v_min_u32_e32 v158, v158, v155
	v_max_u32_e32 v18, v174, v171
	v_min_u32_e32 v174, v174, v171
	v_max_u32_e32 v19, v4, v5
	v_min_u32_e32 v4, v4, v5
	v_max_u32_e32 v131, v144, v141
	v_min_u32_e32 v144, v144, v141
	v_max_u32_e32 v155, v160, v157
	v_min_u32_e32 v160, v160, v157
	v_max_u32_e32 v171, v176, v173
	v_min_u32_e32 v176, v176, v173
	v_max_u32_e32 v5, v6, v7
	v_min_u32_e32 v6, v6, v7
	v_max_u32_e32 v141, v16, v131
	v_min_u32_e32 v16, v16, v131
	v_max_u32_e32 v157, v17, v155
	v_min_u32_e32 v17, v17, v155
	v_max_u32_e32 v173, v18, v171
	v_min_u32_e32 v18, v18, v171
; DI void peer_half_topk(const bf16_t* qrow  , const bf16_t* subk  , int hi, int lane, LAS unsigned* ltop) {
;     ...
; #pragma unroll 1
;     for (int k = 0; k < 16; ++k) {
;         unsigned mx = keys[0];
; #pragma unroll
;         for (int i = 1; i < 64; ++i) mx = mx > keys[i] ? mx : keys[i];
;         const unsigned om = (unsigned)__shfl_xor((int)mx, 32);
;         mx = mx > om ? mx : om;
;         ltop[k * 64 + lane] = mx;
; #pragma unroll
;         for (int i = 0; i < 64; ++i) keys[i] = keys[i] == mx ? 0u : keys[i];
;     }
	v_max_u32_e32 v7, v19, v5
	v_min_u32_e32 v19, v19, v5
	v_max_u32_e32 v131, v142, v144
	v_min_u32_e32 v142, v142, v144
	v_max_u32_e32 v155, v158, v160
	v_min_u32_e32 v158, v158, v160
	v_max_u32_e32 v171, v174, v176
	v_min_u32_e32 v174, v174, v176
	v_max_u32_e32 v5, v4, v6
	v_min_u32_e32 v4, v4, v6
	v_max_u32_e32 v144, v131, v16
	v_min_u32_e32 v131, v131, v16
	v_max_u32_e32 v160, v155, v17
	v_min_u32_e32 v155, v155, v17
	v_max_u32_e32 v176, v171, v18
	v_min_u32_e32 v171, v171, v18
	v_max_u32_e32 v6, v5, v19
	v_min_u32_e32 v5, v5, v19
	v_max_u32_e32 v16, v119, v141
	v_min_u32_e32 v119, v119, v141
	v_max_u32_e32 v17, v153, v157
	v_min_u32_e32 v153, v153, v157
	v_max_u32_e32 v18, v169, v173
	v_min_u32_e32 v169, v169, v173
	v_max_u32_e32 v19, v3, v7
	v_min_u32_e32 v3, v3, v7
	v_max_u32_e32 v141, v49, v131
	v_min_u32_e32 v49, v49, v131
	v_max_u32_e32 v157, v151, v155
	v_min_u32_e32 v151, v151, v155
	v_max_u32_e32 v173, v167, v171
	v_min_u32_e32 v167, v167, v171
	v_max_u32_e32 v7, v1, v5
	v_min_u32_e32 v1, v1, v5
	v_max_u32_e32 v131, v141, v119
	v_min_u32_e32 v141, v141, v119
	v_max_u32_e32 v155, v157, v153
	v_min_u32_e32 v157, v157, v153
	v_max_u32_e32 v171, v173, v169
	v_min_u32_e32 v173, v173, v169
	v_max_u32_e32 v5, v7, v3
	v_min_u32_e32 v7, v7, v3
	v_max_u32_e32 v119, v140, v144
	v_min_u32_e32 v140, v140, v144
	v_max_u32_e32 v153, v156, v160
	v_min_u32_e32 v156, v156, v160
	v_max_u32_e32 v169, v172, v176
	v_min_u32_e32 v172, v172, v176
	v_max_u32_e32 v3, v2, v6
	v_min_u32_e32 v2, v2, v6
	v_max_u32_e32 v144, v128, v142
	v_min_u32_e32 v128, v128, v142
	v_max_u32_e32 v160, v154, v158
	v_min_u32_e32 v154, v154, v158
	v_max_u32_e32 v176, v170, v174
	v_min_u32_e32 v170, v170, v174
	v_max_u32_e32 v6, v0, v4
	v_min_u32_e32 v0, v0, v4
	v_max_u32_e32 v142, v144, v140
	v_min_u32_e32 v144, v144, v140
	v_max_u32_e32 v158, v160, v156
	v_min_u32_e32 v160, v160, v156
	v_max_u32_e32 v174, v176, v172
	v_min_u32_e32 v176, v176, v172
	v_max_u32_e32 v4, v6, v2
	v_min_u32_e32 v6, v6, v2
	v_max_u32_e32 v140, v119, v131
	v_min_u32_e32 v119, v119, v131
	v_max_u32_e32 v156, v153, v155
	v_min_u32_e32 v153, v153, v155
	v_max_u32_e32 v172, v169, v171
	v_min_u32_e32 v169, v169, v171
	v_max_u32_e32 v2, v3, v5
	v_min_u32_e32 v3, v3, v5
	v_max_u32_e32 v131, v142, v141
	v_min_u32_e32 v142, v142, v141
	v_max_u32_e32 v155, v158, v157
	v_min_u32_e32 v158, v158, v157
	v_max_u32_e32 v171, v174, v173
	v_min_u32_e32 v174, v174, v173
	v_max_u32_e32 v5, v4, v7
	v_min_u32_e32 v4, v4, v7
	v_max_u32_e32 v141, v144, v49
	v_min_u32_e32 v144, v144, v49
	v_max_u32_e32 v157, v160, v151
	v_min_u32_e32 v160, v160, v151
	v_max_u32_e32 v173, v176, v167
	v_min_u32_e32 v176, v176, v167
	v_max_u32_e32 v7, v6, v1
	v_min_u32_e32 v6, v6, v1
	v_max_u32_e32 v49, v146, v143
	v_min_u32_e32 v146, v146, v143
	v_max_u32_e32 v151, v162, v159
	v_min_u32_e32 v162, v162, v159
	v_max_u32_e32 v167, v178, v175
	v_min_u32_e32 v178, v178, v175
	v_max_u32_e32 v1, v8, v9
	v_min_u32_e32 v8, v8, v9
	v_max_u32_e32 v143, v148, v145
	v_min_u32_e32 v148, v148, v145
	v_max_u32_e32 v159, v164, v161
	v_min_u32_e32 v164, v164, v161
	v_max_u32_e32 v175, v180, v177
	v_min_u32_e32 v180, v180, v177
	v_max_u32_e32 v9, v10, v11
	v_min_u32_e32 v10, v10, v11
	v_max_u32_e32 v145, v49, v143
	v_min_u32_e32 v49, v49, v143
	v_max_u32_e32 v161, v151, v159
	v_min_u32_e32 v151, v151, v159
	v_max_u32_e32 v177, v167, v175
	v_min_u32_e32 v167, v167, v175
	v_max_u32_e32 v11, v1, v9
	v_min_u32_e32 v1, v1, v9
	v_max_u32_e32 v143, v146, v148
	v_min_u32_e32 v146, v146, v148
	v_max_u32_e32 v159, v162, v164
	v_min_u32_e32 v162, v162, v164
	v_max_u32_e32 v175, v178, v180
	v_min_u32_e32 v178, v178, v180
	v_max_u32_e32 v9, v8, v10
	v_min_u32_e32 v8, v8, v10
	v_max_u32_e32 v148, v143, v49
	v_min_u32_e32 v143, v143, v49
	v_max_u32_e32 v164, v159, v151
	v_min_u32_e32 v159, v159, v151
	v_max_u32_e32 v180, v175, v167
	v_min_u32_e32 v175, v175, v167
	v_max_u32_e32 v10, v9, v1
	v_min_u32_e32 v9, v9, v1
	v_max_u32_e32 v49, v150, v147
	v_min_u32_e32 v150, v150, v147
	v_max_u32_e32 v151, v166, v163
	v_min_u32_e32 v166, v166, v163
	v_max_u32_e32 v167, v182, v179
	v_min_u32_e32 v182, v182, v179
	v_max_u32_e32 v1, v12, v13
	v_min_u32_e32 v12, v12, v13
	v_max_u32_e32 v147, v152, v149
	v_min_u32_e32 v152, v152, v149
	v_max_u32_e32 v163, v168, v165
	v_min_u32_e32 v168, v168, v165
	v_max_u32_e32 v179, v184, v181
	v_min_u32_e32 v184, v184, v181
	v_max_u32_e32 v13, v14, v15
	v_min_u32_e32 v14, v14, v15
	v_max_u32_e32 v149, v49, v147
	v_min_u32_e32 v49, v49, v147
	v_max_u32_e32 v165, v151, v163
	v_min_u32_e32 v151, v151, v163
	v_max_u32_e32 v181, v167, v179
	v_min_u32_e32 v167, v167, v179
	v_max_u32_e32 v15, v1, v13
	v_min_u32_e32 v1, v1, v13
	v_max_u32_e32 v147, v150, v152
	v_min_u32_e32 v150, v150, v152
	v_max_u32_e32 v163, v166, v168
	v_min_u32_e32 v166, v166, v168
	v_max_u32_e32 v179, v182, v184
	v_min_u32_e32 v182, v182, v184
	v_max_u32_e32 v13, v12, v14
	v_min_u32_e32 v12, v12, v14
	v_max_u32_e32 v152, v147, v49
	v_min_u32_e32 v147, v147, v49
	v_max_u32_e32 v168, v163, v151
	v_min_u32_e32 v163, v163, v151
	v_max_u32_e32 v184, v179, v167
	v_min_u32_e32 v179, v179, v167
	v_max_u32_e32 v14, v13, v1
	v_min_u32_e32 v13, v13, v1
	v_max_u32_e32 v49, v145, v149
	v_min_u32_e32 v145, v145, v149
	v_max_u32_e32 v151, v161, v165
	v_min_u32_e32 v161, v161, v165
	v_max_u32_e32 v167, v177, v181
	v_min_u32_e32 v177, v177, v181
	v_max_u32_e32 v1, v11, v15
	v_min_u32_e32 v11, v11, v15
	v_max_u32_e32 v149, v143, v147
	v_min_u32_e32 v143, v143, v147
	v_max_u32_e32 v165, v159, v163
	v_min_u32_e32 v159, v159, v163
	v_max_u32_e32 v181, v175, v179
	v_min_u32_e32 v175, v175, v179
; DI void peer_half_topk(const bf16_t* qrow  , const bf16_t* subk  , int hi, int lane, LAS unsigned* ltop) {
;     ...
; #pragma unroll 1
;     for (int k = 0; k < 16; ++k) {
;         unsigned mx = keys[0];
; #pragma unroll
;         for (int i = 1; i < 64; ++i) mx = mx > keys[i] ? mx : keys[i];
;         const unsigned om = (unsigned)__shfl_xor((int)mx, 32);
;         mx = mx > om ? mx : om;
;         ltop[k * 64 + lane] = mx;
; #pragma unroll
;         for (int i = 0; i < 64; ++i) keys[i] = keys[i] == mx ? 0u : keys[i];
;     }
	v_max_u32_e32 v15, v9, v13
	v_min_u32_e32 v9, v9, v13
	v_max_u32_e32 v147, v149, v145
	v_min_u32_e32 v149, v149, v145
	v_max_u32_e32 v163, v165, v161
	v_min_u32_e32 v165, v165, v161
	v_max_u32_e32 v179, v181, v177
	v_min_u32_e32 v181, v181, v177
	v_max_u32_e32 v13, v15, v11
	v_min_u32_e32 v15, v15, v11
	v_max_u32_e32 v145, v148, v152
	v_min_u32_e32 v148, v148, v152
	v_max_u32_e32 v161, v164, v168
	v_min_u32_e32 v164, v164, v168
	v_max_u32_e32 v177, v180, v184
	v_min_u32_e32 v180, v180, v184
	v_max_u32_e32 v11, v10, v14
	v_min_u32_e32 v10, v10, v14
	v_max_u32_e32 v152, v146, v150
	v_min_u32_e32 v146, v146, v150
	v_max_u32_e32 v168, v162, v166
	v_min_u32_e32 v162, v162, v166
	v_max_u32_e32 v184, v178, v182
	v_min_u32_e32 v178, v178, v182
	v_max_u32_e32 v14, v8, v12
	v_min_u32_e32 v8, v8, v12
	v_max_u32_e32 v150, v152, v148
	v_min_u32_e32 v152, v152, v148
	v_max_u32_e32 v166, v168, v164
	v_min_u32_e32 v168, v168, v164
	v_max_u32_e32 v182, v184, v180
	v_min_u32_e32 v184, v184, v180
	v_max_u32_e32 v12, v14, v10
	v_min_u32_e32 v14, v14, v10
	v_max_u32_e32 v148, v145, v147
	v_min_u32_e32 v145, v145, v147
	v_max_u32_e32 v164, v161, v163
	v_min_u32_e32 v161, v161, v163
	v_max_u32_e32 v180, v177, v179
	v_min_u32_e32 v177, v177, v179
	v_max_u32_e32 v10, v11, v13
	v_min_u32_e32 v11, v11, v13
	v_max_u32_e32 v147, v150, v149
	v_min_u32_e32 v150, v150, v149
	v_max_u32_e32 v163, v166, v165
	v_min_u32_e32 v166, v166, v165
	v_max_u32_e32 v179, v182, v181
	v_min_u32_e32 v182, v182, v181
	v_max_u32_e32 v13, v12, v15
	v_min_u32_e32 v12, v12, v15
	v_max_u32_e32 v149, v152, v143
	v_min_u32_e32 v152, v152, v143
	v_max_u32_e32 v165, v168, v159
	v_min_u32_e32 v168, v168, v159
	v_max_u32_e32 v181, v184, v175
	v_min_u32_e32 v184, v184, v175
	v_max_u32_e32 v15, v14, v9
	v_min_u32_e32 v14, v14, v9
	v_max_u32_e32 v143, v16, v49
	v_min_u32_e32 v16, v16, v49
	v_max_u32_e32 v159, v17, v151
	v_min_u32_e32 v17, v17, v151
	v_max_u32_e32 v175, v18, v167
	v_min_u32_e32 v18, v18, v167
	v_max_u32_e32 v9, v19, v1
	v_min_u32_e32 v19, v19, v1
	v_max_u32_e32 v49, v142, v150
	v_min_u32_e32 v142, v142, v150
	v_max_u32_e32 v151, v158, v166
	v_min_u32_e32 v158, v158, v166
	v_max_u32_e32 v167, v174, v182
	v_min_u32_e32 v174, v174, v182
	v_max_u32_e32 v1, v4, v12
	v_min_u32_e32 v4, v4, v12
	v_max_u32_e32 v150, v49, v16
	v_min_u32_e32 v49, v49, v16
	v_max_u32_e32 v166, v151, v17
	v_min_u32_e32 v151, v151, v17
	v_max_u32_e32 v182, v167, v18
	v_min_u32_e32 v167, v167, v18
	v_max_u32_e32 v12, v1, v19
	v_min_u32_e32 v1, v1, v19
	v_max_u32_e32 v16, v119, v145
	v_min_u32_e32 v119, v119, v145
	v_max_u32_e32 v17, v153, v161
	v_min_u32_e32 v153, v153, v161
	v_max_u32_e32 v18, v169, v177
	v_min_u32_e32 v169, v169, v177
	v_max_u32_e32 v19, v3, v11
	v_min_u32_e32 v3, v3, v11
	v_max_u32_e32 v145, v144, v152
	v_min_u32_e32 v144, v144, v152
	v_max_u32_e32 v161, v160, v168
	v_min_u32_e32 v160, v160, v168
	v_max_u32_e32 v177, v176, v184
	v_min_u32_e32 v176, v176, v184
	v_max_u32_e32 v11, v6, v14
	v_min_u32_e32 v6, v6, v14
	v_max_u32_e32 v152, v145, v119
	v_min_u32_e32 v145, v145, v119
	v_max_u32_e32 v168, v161, v153
	v_min_u32_e32 v161, v161, v153
	v_max_u32_e32 v184, v177, v169
	v_min_u32_e32 v177, v177, v169
	v_max_u32_e32 v14, v11, v3
	v_min_u32_e32 v11, v11, v3
	v_max_u32_e32 v119, v16, v150
	v_min_u32_e32 v16, v16, v150
	v_max_u32_e32 v153, v17, v166
	v_min_u32_e32 v17, v17, v166
	v_max_u32_e32 v169, v18, v182
	v_min_u32_e32 v18, v18, v182
	v_max_u32_e32 v3, v19, v12
	v_min_u32_e32 v19, v19, v12
	v_max_u32_e32 v150, v152, v49
	v_min_u32_e32 v152, v152, v49
	v_max_u32_e32 v166, v168, v151
	v_min_u32_e32 v168, v168, v151
	v_max_u32_e32 v182, v184, v167
	v_min_u32_e32 v184, v184, v167
	v_max_u32_e32 v12, v14, v1
	v_min_u32_e32 v14, v14, v1
	v_max_u32_e32 v49, v145, v142
	v_min_u32_e32 v145, v145, v142
	v_max_u32_e32 v151, v161, v158
	v_min_u32_e32 v161, v161, v158
	v_max_u32_e32 v167, v177, v174
	v_min_u32_e32 v177, v177, v174
	v_max_u32_e32 v1, v11, v4
	v_min_u32_e32 v11, v11, v4
	v_max_u32_e32 v142, v140, v148
	v_min_u32_e32 v140, v140, v148
	v_max_u32_e32 v158, v156, v164
	v_min_u32_e32 v156, v156, v164
	v_max_u32_e32 v174, v172, v180
	v_min_u32_e32 v172, v172, v180
	v_max_u32_e32 v4, v2, v10
	v_min_u32_e32 v2, v2, v10
	v_max_u32_e32 v148, v141, v149
	v_min_u32_e32 v141, v141, v149
	v_max_u32_e32 v164, v157, v165
	v_min_u32_e32 v157, v157, v165
	v_max_u32_e32 v180, v173, v181
	v_min_u32_e32 v173, v173, v181
	v_max_u32_e32 v10, v7, v15
	v_min_u32_e32 v7, v7, v15
	v_max_u32_e32 v149, v148, v140
	v_min_u32_e32 v148, v148, v140
	v_max_u32_e32 v165, v164, v156
	v_min_u32_e32 v164, v164, v156
	v_max_u32_e32 v181, v180, v172
	v_min_u32_e32 v180, v180, v172
	v_max_u32_e32 v15, v10, v2
	v_min_u32_e32 v10, v10, v2
	v_max_u32_e32 v140, v131, v147
	v_min_u32_e32 v131, v131, v147
	v_max_u32_e32 v156, v155, v163
	v_min_u32_e32 v155, v155, v163
	v_max_u32_e32 v172, v171, v179
	v_min_u32_e32 v171, v171, v179
	v_max_u32_e32 v2, v5, v13
	v_min_u32_e32 v5, v5, v13
	v_max_u32_e32 v147, v128, v146
	v_min_u32_e32 v128, v128, v146
	v_max_u32_e32 v163, v154, v162
	v_min_u32_e32 v154, v154, v162
	v_max_u32_e32 v179, v170, v178
	v_min_u32_e32 v170, v170, v178
	v_max_u32_e32 v13, v0, v8
	v_min_u32_e32 v0, v0, v8
	v_max_u32_e32 v146, v147, v131
	v_min_u32_e32 v147, v147, v131
	v_max_u32_e32 v162, v163, v155
	v_min_u32_e32 v163, v163, v155
	v_max_u32_e32 v178, v179, v171
	v_min_u32_e32 v179, v179, v171
	v_max_u32_e32 v8, v13, v5
	v_min_u32_e32 v13, v13, v5
	v_max_u32_e32 v131, v140, v149
	v_min_u32_e32 v140, v140, v149
	v_max_u32_e32 v155, v156, v165
	v_min_u32_e32 v156, v156, v165
	v_max_u32_e32 v171, v172, v181
; DI void peer_half_topk(const bf16_t* qrow  , const bf16_t* subk  , int hi, int lane, LAS unsigned* ltop) {
;     ...
; #pragma unroll 1
;     for (int k = 0; k < 16; ++k) {
;         unsigned mx = keys[0];
; #pragma unroll
;         for (int i = 1; i < 64; ++i) mx = mx > keys[i] ? mx : keys[i];
;         const unsigned om = (unsigned)__shfl_xor((int)mx, 32);
;         mx = mx > om ? mx : om;
;         ltop[k * 64 + lane] = mx;
; #pragma unroll
;         for (int i = 0; i < 64; ++i) keys[i] = keys[i] == mx ? 0u : keys[i];
;     }
	v_min_u32_e32 v172, v172, v181
	v_max_u32_e32 v5, v2, v15
	v_min_u32_e32 v2, v2, v15
	v_max_u32_e32 v149, v146, v148
	v_min_u32_e32 v146, v146, v148
	v_max_u32_e32 v165, v162, v164
	v_min_u32_e32 v162, v162, v164
	v_max_u32_e32 v181, v178, v180
	v_min_u32_e32 v178, v178, v180
	v_max_u32_e32 v15, v8, v10
	v_min_u32_e32 v8, v8, v10
	v_max_u32_e32 v148, v147, v141
	v_min_u32_e32 v147, v147, v141
	v_max_u32_e32 v164, v163, v157
	v_min_u32_e32 v163, v163, v157
	v_max_u32_e32 v180, v179, v173
	v_min_u32_e32 v179, v179, v173
	v_max_u32_e32 v10, v13, v7
	v_min_u32_e32 v13, v13, v7
	v_max_u32_e32 v141, v142, v119
	v_min_u32_e32 v142, v142, v119
	v_max_u32_e32 v157, v158, v153
	v_min_u32_e32 v158, v158, v153
	v_max_u32_e32 v173, v174, v169
	v_min_u32_e32 v174, v174, v169
	v_max_u32_e32 v7, v4, v3
	v_min_u32_e32 v4, v4, v3
	v_max_u32_e32 v119, v131, v16
	v_min_u32_e32 v131, v131, v16
	v_max_u32_e32 v153, v155, v17
	v_min_u32_e32 v155, v155, v17
	v_max_u32_e32 v169, v171, v18
	v_min_u32_e32 v171, v171, v18
	v_max_u32_e32 v3, v5, v19
	v_min_u32_e32 v5, v5, v19
	v_max_u32_e32 v16, v140, v150
	v_min_u32_e32 v140, v140, v150
	v_max_u32_e32 v17, v156, v166
	v_min_u32_e32 v156, v156, v166
	v_max_u32_e32 v18, v172, v182
	v_min_u32_e32 v172, v172, v182
	v_max_u32_e32 v19, v2, v12
	v_min_u32_e32 v2, v2, v12
	v_max_u32_e32 v150, v149, v152
	v_min_u32_e32 v149, v149, v152
	v_max_u32_e32 v166, v165, v168
	v_min_u32_e32 v165, v165, v168
	v_max_u32_e32 v182, v181, v184
	v_min_u32_e32 v181, v181, v184
	v_max_u32_e32 v12, v15, v14
	v_min_u32_e32 v15, v15, v14
	v_max_u32_e32 v152, v146, v49
	v_min_u32_e32 v146, v146, v49
	v_max_u32_e32 v168, v162, v151
	v_min_u32_e32 v162, v162, v151
	v_max_u32_e32 v184, v178, v167
	v_min_u32_e32 v178, v178, v167
	v_max_u32_e32 v14, v8, v1
	v_min_u32_e32 v8, v8, v1
	v_max_u32_e32 v49, v148, v145
	v_min_u32_e32 v148, v148, v145
	v_max_u32_e32 v151, v164, v161
	v_min_u32_e32 v164, v164, v161
	v_max_u32_e32 v167, v180, v177
	v_min_u32_e32 v180, v180, v177
	v_max_u32_e32 v1, v10, v11
	v_min_u32_e32 v10, v10, v11
	v_max_u32_e32 v145, v147, v144
	v_min_u32_e32 v147, v147, v144
	v_max_u32_e32 v161, v163, v160
	v_min_u32_e32 v163, v163, v160
	v_max_u32_e32 v177, v179, v176
	v_min_u32_e32 v179, v179, v176
	v_max_u32_e32 v11, v13, v6
	v_min_u32_e32 v13, v13, v6
	v_max_u32_e32 v143, v143, v154
	v_max_u32_e32 v175, v175, v0
	v_max_u32_e32 v141, v141, v163
	v_max_u32_e32 v173, v173, v13
	v_max_u32_e32 v142, v142, v161
	v_max_u32_e32 v174, v174, v11
	v_max_u32_e32 v119, v119, v164
	v_max_u32_e32 v169, v169, v10
	v_max_u32_e32 v131, v131, v151
	v_max_u32_e32 v171, v171, v1
	v_max_u32_e32 v16, v16, v162
	v_max_u32_e32 v18, v18, v8
	v_max_u32_e32 v140, v140, v168
	v_max_u32_e32 v172, v172, v14
	v_max_u32_e32 v150, v150, v165
	v_max_u32_e32 v182, v182, v15
	v_max_u32_e32 v149, v149, v166
	v_max_u32_e32 v181, v181, v12
	v_max_u32_e32 v152, v152, v156
	v_max_u32_e32 v184, v184, v2
	v_max_u32_e32 v146, v146, v17
	v_max_u32_e32 v178, v178, v19
	v_max_u32_e32 v49, v49, v155
	v_max_u32_e32 v167, v167, v5
	v_max_u32_e32 v148, v148, v153
	v_max_u32_e32 v180, v180, v3
	v_max_u32_e32 v145, v145, v158
	v_max_u32_e32 v177, v177, v4
	v_max_u32_e32 v147, v147, v157
	v_max_u32_e32 v179, v179, v7
	v_max_u32_e32 v128, v128, v159
	v_max_u32_e32 v170, v170, v9
	v_max_u32_e32 v144, v143, v149
	v_min_u32_e32 v143, v143, v149
	v_max_u32_e32 v176, v175, v181
	v_min_u32_e32 v175, v175, v181
	v_max_u32_e32 v149, v141, v152
	v_min_u32_e32 v141, v141, v152
	v_max_u32_e32 v181, v173, v184
	v_min_u32_e32 v173, v173, v184
	v_max_u32_e32 v152, v142, v146
	v_min_u32_e32 v142, v142, v146
	v_max_u32_e32 v184, v174, v178
	v_min_u32_e32 v174, v174, v178
	v_max_u32_e32 v146, v119, v49
	v_min_u32_e32 v119, v119, v49
	v_max_u32_e32 v178, v169, v167
	v_min_u32_e32 v169, v169, v167
	v_max_u32_e32 v49, v131, v148
	v_min_u32_e32 v131, v131, v148
	v_max_u32_e32 v167, v171, v180
	v_min_u32_e32 v171, v171, v180
	v_max_u32_e32 v148, v16, v145
	v_min_u32_e32 v16, v16, v145
	v_max_u32_e32 v180, v18, v177
	v_min_u32_e32 v18, v18, v177
	v_max_u32_e32 v145, v140, v147
	v_min_u32_e32 v140, v140, v147
	v_max_u32_e32 v177, v172, v179
	v_min_u32_e32 v172, v172, v179
	v_max_u32_e32 v147, v150, v128
	v_min_u32_e32 v150, v150, v128
	v_max_u32_e32 v179, v182, v170
	v_min_u32_e32 v182, v182, v170
	v_max_u32_e32 v128, v144, v49
	v_min_u32_e32 v144, v144, v49
	v_max_u32_e32 v170, v176, v167
	v_min_u32_e32 v176, v176, v167
	v_max_u32_e32 v49, v149, v148
	v_min_u32_e32 v149, v149, v148
	v_max_u32_e32 v167, v181, v180
	v_min_u32_e32 v181, v181, v180
	v_max_u32_e32 v148, v152, v145
	v_min_u32_e32 v152, v152, v145
	v_max_u32_e32 v180, v184, v177
	v_min_u32_e32 v184, v184, v177
	v_max_u32_e32 v145, v146, v147
	v_min_u32_e32 v146, v146, v147
	v_max_u32_e32 v177, v178, v179
	v_min_u32_e32 v178, v178, v179
	v_max_u32_e32 v147, v143, v131
	v_min_u32_e32 v143, v143, v131
	v_max_u32_e32 v179, v175, v171
	v_min_u32_e32 v175, v175, v171
	v_max_u32_e32 v131, v141, v16
	v_min_u32_e32 v141, v141, v16
	v_max_u32_e32 v171, v173, v18
	v_min_u32_e32 v173, v173, v18
	v_max_u32_e32 v16, v142, v140
	v_min_u32_e32 v142, v142, v140
	v_max_u32_e32 v18, v174, v172
	v_min_u32_e32 v174, v174, v172
	v_max_u32_e32 v140, v119, v150
	v_min_u32_e32 v119, v119, v150
	v_max_u32_e32 v172, v169, v182
	v_min_u32_e32 v169, v169, v182
	v_max_u32_e32 v150, v128, v148
	v_min_u32_e32 v128, v128, v148
	v_max_u32_e32 v182, v170, v180
	v_min_u32_e32 v170, v170, v180
	v_max_u32_e32 v148, v49, v145
	v_min_u32_e32 v49, v49, v145
	v_max_u32_e32 v180, v167, v177
	v_min_u32_e32 v167, v167, v177
	v_max_u32_e32 v145, v144, v152
	v_min_u32_e32 v144, v144, v152
; DI void peer_half_topk(const bf16_t* qrow  , const bf16_t* subk  , int hi, int lane, LAS unsigned* ltop) {
;     ...
; #pragma unroll 1
;     for (int k = 0; k < 16; ++k) {
;         unsigned mx = keys[0];
; #pragma unroll
;         for (int i = 1; i < 64; ++i) mx = mx > keys[i] ? mx : keys[i];
;         const unsigned om = (unsigned)__shfl_xor((int)mx, 32);
;         mx = mx > om ? mx : om;
;         ltop[k * 64 + lane] = mx;
; #pragma unroll
;         for (int i = 0; i < 64; ++i) keys[i] = keys[i] == mx ? 0u : keys[i];
;     }
	v_max_u32_e32 v177, v176, v184
	v_min_u32_e32 v176, v176, v184
	v_max_u32_e32 v152, v149, v146
	v_min_u32_e32 v149, v149, v146
	v_max_u32_e32 v184, v181, v178
	v_min_u32_e32 v181, v181, v178
	v_max_u32_e32 v146, v147, v16
	v_min_u32_e32 v147, v147, v16
	v_max_u32_e32 v178, v179, v18
	v_min_u32_e32 v179, v179, v18
	v_max_u32_e32 v16, v131, v140
	v_min_u32_e32 v131, v131, v140
	v_max_u32_e32 v18, v171, v172
	v_min_u32_e32 v171, v171, v172
	v_max_u32_e32 v140, v143, v142
	v_min_u32_e32 v143, v143, v142
	v_max_u32_e32 v172, v175, v174
	v_min_u32_e32 v175, v175, v174
	v_max_u32_e32 v142, v141, v119
	v_min_u32_e32 v141, v141, v119
	v_max_u32_e32 v174, v173, v169
	v_min_u32_e32 v173, v173, v169
	v_max_u32_e32 v119, v150, v148
	v_min_u32_e32 v150, v150, v148
	v_max_u32_e32 v169, v182, v180
	v_min_u32_e32 v182, v182, v180
	v_max_u32_e32 v148, v128, v49
	v_min_u32_e32 v128, v128, v49
	v_max_u32_e32 v180, v170, v167
	v_min_u32_e32 v170, v170, v167
	v_max_u32_e32 v49, v145, v152
	v_min_u32_e32 v145, v145, v152
	v_max_u32_e32 v167, v177, v184
	v_min_u32_e32 v177, v177, v184
	v_max_u32_e32 v152, v144, v149
	v_min_u32_e32 v144, v144, v149
	v_max_u32_e32 v184, v176, v181
	v_min_u32_e32 v176, v176, v181
	v_max_u32_e32 v149, v146, v16
	v_min_u32_e32 v146, v146, v16
	v_max_u32_e32 v181, v178, v18
	v_min_u32_e32 v178, v178, v18
	v_max_u32_e32 v16, v147, v131
	v_min_u32_e32 v147, v147, v131
	v_max_u32_e32 v18, v179, v171
	v_min_u32_e32 v179, v179, v171
	v_max_u32_e32 v131, v140, v142
	v_min_u32_e32 v140, v140, v142
	v_max_u32_e32 v171, v172, v174
	v_min_u32_e32 v172, v172, v174
	v_max_u32_e32 v142, v143, v141
	v_min_u32_e32 v143, v143, v141
	v_max_u32_e32 v174, v175, v173
	v_min_u32_e32 v175, v175, v173
	v_max_u32_e32 v119, v119, v175
	v_max_u32_e32 v150, v150, v174
	v_max_u32_e32 v148, v148, v172
	v_max_u32_e32 v128, v128, v171
	v_max_u32_e32 v49, v49, v179
	v_max_u32_e32 v145, v145, v18
	v_max_u32_e32 v152, v152, v178
	v_max_u32_e32 v144, v144, v181
	v_max_u32_e32 v149, v149, v176
	v_max_u32_e32 v146, v146, v184
	v_max_u32_e32 v16, v16, v177
	v_max_u32_e32 v147, v147, v167
	v_max_u32_e32 v131, v131, v170
	v_max_u32_e32 v140, v140, v180
	v_max_u32_e32 v142, v142, v182
	v_max_u32_e32 v143, v143, v169
	v_max_u32_e32 v141, v119, v149
	v_min_u32_e32 v119, v119, v149
	v_max_u32_e32 v149, v150, v146
	v_min_u32_e32 v150, v150, v146
	v_max_u32_e32 v146, v148, v16
	v_min_u32_e32 v148, v148, v16
	v_max_u32_e32 v16, v128, v147
	v_min_u32_e32 v128, v128, v147
	v_max_u32_e32 v147, v49, v131
	v_min_u32_e32 v49, v49, v131
	v_max_u32_e32 v131, v145, v140
	v_min_u32_e32 v145, v145, v140
	v_max_u32_e32 v140, v152, v142
	v_min_u32_e32 v152, v152, v142
	v_max_u32_e32 v142, v144, v143
	v_min_u32_e32 v144, v144, v143
	v_max_u32_e32 v143, v141, v147
	v_min_u32_e32 v141, v141, v147
	v_max_u32_e32 v147, v149, v131
	v_min_u32_e32 v149, v149, v131
	v_max_u32_e32 v131, v146, v140
	v_min_u32_e32 v146, v146, v140
	v_max_u32_e32 v140, v16, v142
	v_min_u32_e32 v16, v16, v142
	v_max_u32_e32 v142, v119, v49
	v_min_u32_e32 v119, v119, v49
	v_max_u32_e32 v49, v150, v145
	v_min_u32_e32 v150, v150, v145
	v_max_u32_e32 v145, v148, v152
	v_min_u32_e32 v148, v148, v152
	v_max_u32_e32 v152, v128, v144
	v_min_u32_e32 v128, v128, v144
	v_max_u32_e32 v144, v143, v131
	v_min_u32_e32 v143, v143, v131
	v_max_u32_e32 v131, v147, v140
	v_min_u32_e32 v147, v147, v140
	v_max_u32_e32 v140, v141, v146
	v_min_u32_e32 v141, v141, v146
	v_max_u32_e32 v146, v149, v16
	v_min_u32_e32 v149, v149, v16
	v_max_u32_e32 v16, v142, v145
	v_min_u32_e32 v142, v142, v145
	v_max_u32_e32 v145, v49, v152
	v_min_u32_e32 v49, v49, v152
	v_max_u32_e32 v152, v119, v148
	v_min_u32_e32 v119, v119, v148
	v_max_u32_e32 v148, v150, v128
	v_min_u32_e32 v150, v150, v128
	v_max_u32_e32 v128, v144, v131
	v_min_u32_e32 v144, v144, v131
	v_max_u32_e32 v131, v143, v147
	v_min_u32_e32 v143, v143, v147
	v_max_u32_e32 v147, v140, v146
	v_min_u32_e32 v140, v140, v146
	v_max_u32_e32 v146, v141, v149
	v_min_u32_e32 v141, v141, v149
	v_max_u32_e32 v149, v16, v145
	v_min_u32_e32 v16, v16, v145
	v_max_u32_e32 v145, v142, v49
	v_min_u32_e32 v142, v142, v49
	v_max_u32_e32 v49, v152, v148
	v_min_u32_e32 v152, v152, v148
	v_max_u32_e32 v148, v119, v150
	v_min_u32_e32 v119, v119, v150
	ds_bpermute_b32 v154, v188, v128
	ds_bpermute_b32 v151, v188, v144
	ds_bpermute_b32 v156, v188, v131
	ds_bpermute_b32 v153, v188, v143
	ds_bpermute_b32 v158, v188, v147
	ds_bpermute_b32 v155, v188, v140
	ds_bpermute_b32 v160, v188, v146
	ds_bpermute_b32 v157, v188, v141
	ds_bpermute_b32 v162, v188, v149
	ds_bpermute_b32 v159, v188, v16
	ds_bpermute_b32 v164, v188, v145
	ds_bpermute_b32 v161, v188, v142
	ds_bpermute_b32 v166, v188, v49
	ds_bpermute_b32 v163, v188, v152
	ds_bpermute_b32 v168, v188, v148
	ds_bpermute_b32 v165, v188, v119
	s_waitcnt lgkmcnt(0)
; #define LDS_WAIT() asm volatile("s_waitcnt lgkmcnt(0)" ::: "memory")
; DI unsigned ordf(float f) { const unsigned u = __builtin_bit_cast(unsigned, f); return (u & 0x80000000u) ? ~u : (u | 0x80000000u); }
; DI void peer_half_topk(const bf16_t* qrow  , const bf16_t* subk  , int hi, int lane, LAS unsigned* ltop) {
;     ...
; #pragma unroll 1
;     for (int k = 0; k < 16; ++k) {
;         unsigned mx = keys[0];
; #pragma unroll
;         for (int i = 1; i < 64; ++i) mx = mx > keys[i] ? mx : keys[i];
;         const unsigned om = (unsigned)__shfl_xor((int)mx, 32);
;         mx = mx > om ? mx : om;
;         ltop[k * 64 + lane] = mx;
; #pragma unroll
;         for (int i = 0; i < 64; ++i) keys[i] = keys[i] == mx ? 0u : keys[i];
;     }
; DI void phase_peer_select(const Args& a, int layer, LAS unsigned char* lds) {
;     ...
;         LDS_WAIT();
;         unsigned t1[16], t2[16];
; #pragma unroll
;         for (int i = 0; i < 16; ++i) { t1[i] = lt1[i * 64 + lane]; t2[i] = lt2[i * 64 + lane]; }
;         unsigned ck[16][16];
; #pragma unroll
;         for (int x = 0; x < 16; ++x)
; #pragma unroll
;             for (int y = 0; y < 16; ++y)
;                 if ((x + 1) * (y + 1) <= 16) ck[x][y] = (ordf(unordf(t1[x] & ~0x7Fu) + unordf(t2[y] & ~0x7Fu)) & ~0xFFu) | (unsigned)(255 - (x * 16 + y));
	v_max_u32_e32 v128, v128, v165
	v_max_u32_e32 v144, v144, v168
	v_max_u32_e32 v131, v131, v163
	v_max_u32_e32 v143, v143, v166
	v_max_u32_e32 v147, v147, v161
	v_max_u32_e32 v140, v140, v164
	v_max_u32_e32 v146, v146, v159
	v_max_u32_e32 v141, v141, v162
	v_max_u32_e32 v149, v149, v157
	v_max_u32_e32 v16, v16, v160
	v_max_u32_e32 v145, v145, v155
	v_max_u32_e32 v142, v142, v158
	v_max_u32_e32 v49, v49, v153
	v_max_u32_e32 v152, v152, v156
	v_max_u32_e32 v148, v148, v151
	v_max_u32_e32 v119, v119, v154
	v_max_u32_e32 v150, v128, v149
	v_min_u32_e32 v128, v128, v149
	v_max_u32_e32 v149, v144, v16
	v_min_u32_e32 v144, v144, v16
	v_max_u32_e32 v16, v131, v145
	v_min_u32_e32 v131, v131, v145
	v_max_u32_e32 v145, v143, v142
	v_min_u32_e32 v143, v143, v142
	v_max_u32_e32 v142, v147, v49
	v_min_u32_e32 v147, v147, v49
	v_max_u32_e32 v49, v140, v152
	v_min_u32_e32 v140, v140, v152
	v_max_u32_e32 v152, v146, v148
	v_min_u32_e32 v146, v146, v148
	v_max_u32_e32 v148, v141, v119
	v_min_u32_e32 v141, v141, v119
	v_max_u32_e32 v119, v150, v142
	v_min_u32_e32 v150, v150, v142
	v_max_u32_e32 v142, v149, v49
	v_min_u32_e32 v149, v149, v49
	v_max_u32_e32 v49, v16, v152
	v_min_u32_e32 v16, v16, v152
	v_max_u32_e32 v152, v145, v148
	v_min_u32_e32 v145, v145, v148
	v_max_u32_e32 v148, v128, v147
	v_min_u32_e32 v128, v128, v147
	v_max_u32_e32 v147, v144, v140
	v_min_u32_e32 v144, v144, v140
	v_max_u32_e32 v140, v131, v146
	v_min_u32_e32 v131, v131, v146
	v_max_u32_e32 v146, v143, v141
	v_min_u32_e32 v143, v143, v141
	v_max_u32_e32 v141, v119, v49
	v_min_u32_e32 v119, v119, v49
	v_max_u32_e32 v49, v142, v152
	v_min_u32_e32 v142, v142, v152
	v_max_u32_e32 v152, v150, v16
	v_min_u32_e32 v150, v150, v16
	v_max_u32_e32 v16, v149, v145
	v_min_u32_e32 v149, v149, v145
	v_max_u32_e32 v145, v148, v140
	v_min_u32_e32 v148, v148, v140
	v_max_u32_e32 v140, v147, v146
	v_min_u32_e32 v147, v147, v146
	v_max_u32_e32 v146, v128, v131
	v_min_u32_e32 v128, v128, v131
	v_max_u32_e32 v131, v144, v143
	v_min_u32_e32 v144, v144, v143
	v_max_u32_e32 v143, v141, v49
	v_min_u32_e32 v141, v141, v49
	v_max_u32_e32 v49, v119, v142
	v_min_u32_e32 v119, v119, v142
	v_max_u32_e32 v142, v152, v16
	v_min_u32_e32 v152, v152, v16
	v_max_u32_e32 v16, v150, v149
	v_min_u32_e32 v150, v150, v149
	v_max_u32_e32 v149, v145, v140
	v_min_u32_e32 v145, v145, v140
	v_max_u32_e32 v140, v148, v147
	v_min_u32_e32 v148, v148, v147
	v_max_u32_e32 v147, v146, v131
	v_min_u32_e32 v146, v146, v131
	v_max_u32_e32 v131, v128, v144
	v_min_u32_e32 v128, v128, v144
	ds_write_b32 v217, v143
	ds_write_b32 v217, v141 offset:256
	ds_write_b32 v217, v49 offset:512
	ds_write_b32 v217, v119 offset:768
	ds_write_b32 v217, v142 offset:1024
	ds_write_b32 v217, v152 offset:1280
	ds_write_b32 v217, v16 offset:1536
	ds_write_b32 v217, v150 offset:1792
	ds_write_b32 v217, v149 offset:2048
	ds_write_b32 v217, v145 offset:2304
	ds_write_b32 v217, v140 offset:2560
	ds_write_b32 v217, v148 offset:2816
	ds_write_b32 v217, v147 offset:3072
	ds_write_b32 v217, v146 offset:3328
	ds_write_b32 v217, v131 offset:3584
	ds_write_b32 v217, v128 offset:3840
	s_waitcnt lgkmcnt(0)
	ds_read2st64_b32 v[8:9], v216 offset1:1
	ds_read2st64_b32 v[16:17], v216 offset0:2 offset1:3
	ds_read2st64_b32 v[30:31], v216 offset0:4 offset1:5
	ds_read2st64_b32 v[14:15], v216 offset0:6 offset1:7
	ds_read2st64_b32 v[12:13], v216 offset0:16 offset1:17
	ds_read2st64_b32 v[34:35], v216 offset0:18 offset1:19
	ds_read2st64_b32 v[24:25], v216 offset0:20 offset1:21
	ds_read2st64_b32 v[10:11], v216 offset0:22 offset1:23
	ds_read2st64_b32 v[32:33], v216 offset0:8 offset1:9
	ds_read2st64_b32 v[28:29], v216 offset0:10 offset1:11
	ds_read2st64_b32 v[22:23], v216 offset0:12 offset1:13
	ds_read2st64_b32 v[18:19], v216 offset0:14 offset1:15
	ds_read2st64_b32 v[0:1], v216 offset0:24 offset1:25
	ds_read2st64_b32 v[2:3], v216 offset0:26 offset1:27
	ds_read2st64_b32 v[4:5], v216 offset0:28 offset1:29
	ds_read2st64_b32 v[6:7], v216 offset0:30 offset1:31
	s_waitcnt lgkmcnt(14)
	v_and_b32_e32 v20, 0x7fffff80, v8
	v_bitop3_b32 v21, v8, s13, v8 bitop3:0xcf
	v_cmp_gt_i32_e32 vcc, 0, v8
	s_waitcnt lgkmcnt(10)
	v_and_b32_e32 v8, 0x7fffff80, v34
	s_waitcnt lgkmcnt(3)
	v_and_b32_e32 v26, 0x7fffff80, v1
	v_cndmask_b32_e32 v36, v21, v20, vcc
	v_bitop3_b32 v20, v34, s13, v34 bitop3:0xcf
	v_cmp_gt_i32_e32 vcc, 0, v34
	v_and_b32_e32 v21, 0xffffff80, v1
	v_xor_b32_e32 v21, -1, v21
	v_cndmask_b32_e32 v40, v20, v8, vcc
	v_and_b32_e32 v8, 0x7fffff80, v25
	v_bitop3_b32 v20, v25, s13, v25 bitop3:0xcf
	v_cmp_gt_i32_e32 vcc, 0, v25
	v_and_b32_e32 v25, 0x7fffff80, v0
	v_mov_b32_e32 v149, v40
	v_cndmask_b32_e32 v20, v20, v8, vcc
	v_and_b32_e32 v8, 0xffffff80, v0
	v_xor_b32_e32 v8, -1, v8
	v_cmp_gt_i32_e32 vcc, 0, v0
	v_and_b32_e32 v43, 0x7fffff80, v30
	s_movk_i32 s0, 0xff
	v_cndmask_b32_e32 v27, v8, v25, vcc
	v_cmp_gt_i32_e32 vcc, 0, v1
	s_waitcnt lgkmcnt(2)
	v_and_b32_e32 v25, 0x7fffff80, v2
	v_cndmask_b32_e32 v26, v21, v26, vcc
	v_pk_add_f32 v[0:1], v[36:37], v[26:27] op_sel_hi:[0,1]
	v_and_b32_e32 v27, 0x7fffffff, v1
	v_and_b32_e32 v26, 0x7fffffff, v0
	v_xor_b32_e32 v8, -1, v1
	v_pk_add_f32 v[26:27], v[26:27], 0 neg_lo:[1,1] neg_hi:[1,1]
	v_cmp_gt_i32_e32 vcc, 0, v1
	v_xor_b32_e32 v21, -1, v0
	s_nop 0
	v_cndmask_b32_e32 v1, v27, v8, vcc
	v_cmp_gt_i32_e32 vcc, 0, v0
	v_and_b32_e32 v8, 0xffffff80, v2
	v_xor_b32_e32 v8, -1, v8
	v_cndmask_b32_e32 v0, v26, v21, vcc
	v_and_b32_e32 v21, 0xffffff80, v3
	v_cmp_gt_i32_e32 vcc, 0, v2
	v_and_b32_e32 v26, 0x7fffff80, v3
	v_xor_b32_e32 v21, -1, v21
	v_cndmask_b32_e32 v27, v8, v25, vcc
	v_cmp_gt_i32_e32 vcc, 0, v3
	s_waitcnt lgkmcnt(1)
; DI unsigned ordf(float f) { const unsigned u = __builtin_bit_cast(unsigned, f); return (u & 0x80000000u) ? ~u : (u | 0x80000000u); }
; DI void phase_peer_select(const Args& a, int layer, LAS unsigned char* lds) {
;     ...
;         for (int x = 0; x < 16; ++x)
; #pragma unroll
;             for (int y = 0; y < 16; ++y)
;                 if ((x + 1) * (y + 1) <= 16) ck[x][y] = (ordf(unordf(t1[x] & ~0x7Fu) + unordf(t2[y] & ~0x7Fu)) & ~0xFFu) | (unsigned)(255 - (x * 16 + y));
	v_and_b32_e32 v25, 0x7fffff80, v4
	v_and_b32_e32 v1, 0xffffff00, v1
	v_cndmask_b32_e32 v26, v21, v26, vcc
	v_pk_add_f32 v[2:3], v[36:37], v[26:27] op_sel_hi:[0,1]
	v_and_b32_e32 v27, 0x7fffffff, v3
	v_and_b32_e32 v26, 0x7fffffff, v2
	v_xor_b32_e32 v8, -1, v3
	v_pk_add_f32 v[26:27], v[26:27], 0 neg_lo:[1,1] neg_hi:[1,1]
	v_cmp_gt_i32_e32 vcc, 0, v3
	v_xor_b32_e32 v21, -1, v2
	v_and_b32_e32 v0, 0xffffff00, v0
	v_cndmask_b32_e32 v3, v27, v8, vcc
	v_cmp_gt_i32_e32 vcc, 0, v2
	v_and_b32_e32 v8, 0xffffff80, v4
	v_xor_b32_e32 v8, -1, v8
	v_cndmask_b32_e32 v2, v26, v21, vcc
	v_and_b32_e32 v21, 0xffffff80, v5
	v_cmp_gt_i32_e32 vcc, 0, v4
	v_and_b32_e32 v26, 0x7fffff80, v5
	v_xor_b32_e32 v21, -1, v21
	v_cndmask_b32_e32 v27, v8, v25, vcc
	v_cmp_gt_i32_e32 vcc, 0, v5
	s_waitcnt lgkmcnt(0)
	v_and_b32_e32 v25, 0x7fffff80, v6
	v_and_b32_e32 v3, 0xffffff00, v3
	v_cndmask_b32_e32 v26, v21, v26, vcc
	v_pk_add_f32 v[4:5], v[36:37], v[26:27] op_sel_hi:[0,1]
	v_and_b32_e32 v27, 0x7fffffff, v5
	v_and_b32_e32 v26, 0x7fffffff, v4
	v_xor_b32_e32 v8, -1, v5
	v_pk_add_f32 v[26:27], v[26:27], 0 neg_lo:[1,1] neg_hi:[1,1]
	v_cmp_gt_i32_e32 vcc, 0, v5
	v_xor_b32_e32 v21, -1, v4
	v_and_b32_e32 v2, 0xffffff00, v2
	v_cndmask_b32_e32 v5, v27, v8, vcc
	v_cmp_gt_i32_e32 vcc, 0, v4
	v_and_b32_e32 v8, 0xffffff80, v6
	v_xor_b32_e32 v8, -1, v8
	v_cndmask_b32_e32 v4, v26, v21, vcc
	v_and_b32_e32 v21, 0xffffff80, v7
	v_cmp_gt_i32_e32 vcc, 0, v6
	v_and_b32_e32 v26, 0x7fffff80, v7
	v_xor_b32_e32 v21, -1, v21
	v_cndmask_b32_e32 v27, v8, v25, vcc
	v_cmp_gt_i32_e32 vcc, 0, v7
	v_and_b32_e32 v25, 0x7fffff80, v11
	v_and_b32_e32 v5, 0xffffff00, v5
	v_cndmask_b32_e32 v26, v21, v26, vcc
	v_pk_add_f32 v[6:7], v[36:37], v[26:27] op_sel_hi:[0,1]
	v_and_b32_e32 v27, 0x7fffffff, v7
	v_and_b32_e32 v26, 0x7fffffff, v6
	v_xor_b32_e32 v8, -1, v7
	v_pk_add_f32 v[26:27], v[26:27], 0 neg_lo:[1,1] neg_hi:[1,1]
	v_cmp_gt_i32_e32 vcc, 0, v7
	v_xor_b32_e32 v21, -1, v6
	v_and_b32_e32 v4, 0xffffff00, v4
	v_cndmask_b32_e32 v7, v27, v8, vcc
	v_cmp_gt_i32_e32 vcc, 0, v6
	v_and_b32_e32 v8, 0x7fffff80, v9
	v_and_b32_e32 v7, 0xffffff00, v7
	v_cndmask_b32_e32 v6, v26, v21, vcc
	v_bitop3_b32 v21, v9, s13, v9 bitop3:0xcf
	v_cmp_gt_i32_e32 vcc, 0, v9
	v_and_b32_e32 v9, 0xffffff80, v11
	v_xor_b32_e32 v9, -1, v9
	v_cndmask_b32_e32 v34, v21, v8, vcc
	v_and_b32_e32 v8, 0xffffff80, v10
	v_and_b32_e32 v21, 0x7fffff80, v10
	v_xor_b32_e32 v8, -1, v8
	v_cmp_gt_i32_e32 vcc, 0, v10
	v_and_b32_e32 v6, 0xffffff00, v6
	v_or_b32_e32 v1, 0xf7, v1
	v_cndmask_b32_e32 v27, v8, v21, vcc
	v_cmp_gt_i32_e32 vcc, 0, v11
	v_or_b32_e32 v0, 0xf6, v0
	v_or_b32_e32 v3, 0xf5, v3
	v_cndmask_b32_e32 v26, v9, v25, vcc
	v_pk_add_f32 v[8:9], v[36:37], v[26:27] op_sel_hi:[0,1]
	v_and_b32_e32 v11, 0x7fffffff, v9
	v_and_b32_e32 v10, 0x7fffffff, v8
	v_xor_b32_e32 v21, -1, v9
	v_pk_add_f32 v[10:11], v[10:11], 0 neg_lo:[1,1] neg_hi:[1,1]
	v_cmp_gt_i32_e32 vcc, 0, v9
	v_xor_b32_e32 v25, -1, v8
	v_or_b32_e32 v2, 0xf4, v2
	v_cndmask_b32_e32 v9, v11, v21, vcc
	v_cmp_gt_i32_e32 vcc, 0, v8
	v_and_b32_e32 v9, 0xffffff00, v9
	v_or_b32_e32 v5, 0xf3, v5
	v_cndmask_b32_e32 v8, v10, v25, vcc
	v_pk_add_f32 v[10:11], v[34:35], v[26:27] op_sel_hi:[0,1]
	v_and_b32_e32 v27, 0x7fffffff, v11
	v_and_b32_e32 v26, 0x7fffffff, v10
	v_xor_b32_e32 v21, -1, v11
	v_pk_add_f32 v[26:27], v[26:27], 0 neg_lo:[1,1] neg_hi:[1,1]
	v_cmp_gt_i32_e32 vcc, 0, v11
	v_xor_b32_e32 v25, -1, v10
	v_and_b32_e32 v8, 0xffffff00, v8
	v_cndmask_b32_e32 v11, v27, v21, vcc
	v_cmp_gt_i32_e32 vcc, 0, v10
	v_and_b32_e32 v21, 0x7fffff80, v16
	v_and_b32_e32 v27, 0x7fffff80, v13
	v_cndmask_b32_e32 v10, v26, v25, vcc
	v_bitop3_b32 v25, v16, s13, v16 bitop3:0xcf
	v_cmp_gt_i32_e32 vcc, 0, v16
	v_and_b32_e32 v16, 0x7fffff80, v31
	v_and_b32_e32 v26, 0x7fffff80, v15
	v_cndmask_b32_e32 v38, v25, v21, vcc
	v_bitop3_b32 v21, v31, s13, v31 bitop3:0xcf
	v_cmp_gt_i32_e32 vcc, 0, v31
	v_and_b32_e32 v25, 0x7fffff80, v12
	v_and_b32_e32 v11, 0xffffff00, v11
	v_cndmask_b32_e32 v42, v21, v16, vcc
	v_and_b32_e32 v16, 0x7fffff80, v14
	v_bitop3_b32 v21, v14, s13, v14 bitop3:0xcf
	v_cmp_gt_i32_e32 vcc, 0, v14
	v_and_b32_e32 v14, 0xffffff80, v13
	v_xor_b32_e32 v14, -1, v14
	v_cndmask_b32_e32 v44, v21, v16, vcc
	v_and_b32_e32 v16, 0xffffff80, v12
	v_and_b32_e32 v21, 0xffffff80, v15
	v_xor_b32_e32 v16, -1, v16
	v_cmp_gt_i32_e32 vcc, 0, v12
	v_xor_b32_e32 v21, -1, v21
	v_and_b32_e32 v10, 0xffffff00, v10
	v_cndmask_b32_e32 v141, v16, v25, vcc
	v_cmp_gt_i32_e32 vcc, 0, v15
	v_mov_b32_e32 v143, v141
	v_and_b32_e32 v25, 0x7fffff80, v24
	v_cndmask_b32_e32 v140, v21, v26, vcc
	v_cmp_gt_i32_e32 vcc, 0, v13
	v_mov_b32_e32 v47, v140
	v_or_b32_e32 v4, 0xf2, v4
	v_cndmask_b32_e32 v46, v14, v27, vcc
	v_mov_b32_e32 v142, v46
	v_pk_add_f32 v[12:13], v[36:37], v[142:143] op_sel_hi:[0,1]
	v_not_b32_e32 v14, v13
	v_or_b32_e32 v15, 0x80000000, v13
	v_cmp_gt_i32_e32 vcc, 0, v13
	v_not_b32_e32 v13, v12
	v_mov_b32_e32 v41, v46
	v_cndmask_b32_e32 v131, v15, v14, vcc
	v_or_b32_e32 v14, 0x80000000, v12
	v_cmp_gt_i32_e32 vcc, 0, v12
	v_pk_add_f32 v[46:47], v[140:141], v[46:47]
	v_or_b32_e32 v7, 0xf1, v7
	v_cndmask_b32_e32 v12, v14, v13, vcc
	v_and_b32_e32 v12, 0xffffff00, v12
	v_or_b32_e32 v119, 0xfe, v12
	v_pk_add_f32 v[12:13], v[34:35], v[142:143] op_sel_hi:[0,1]
	v_and_b32_e32 v15, 0x7fffffff, v13
	v_and_b32_e32 v14, 0x7fffffff, v12
	v_xor_b32_e32 v16, -1, v13
	v_pk_add_f32 v[14:15], v[14:15], 0 neg_lo:[1,1] neg_hi:[1,1]
	v_cmp_gt_i32_e32 vcc, 0, v13
	v_xor_b32_e32 v21, -1, v12
	v_or_b32_e32 v6, 0xf0, v6
	v_cndmask_b32_e32 v13, v15, v16, vcc
	v_cmp_gt_i32_e32 vcc, 0, v12
	v_and_b32_e32 v13, 0xffffff00, v13
	v_or_b32_e32 v9, 0xf9, v9
	v_cndmask_b32_e32 v12, v14, v21, vcc
; DI unsigned ordf(float f) { const unsigned u = __builtin_bit_cast(unsigned, f); return (u & 0x80000000u) ? ~u : (u | 0x80000000u); }
; DI void phase_peer_select(const Args& a, int layer, LAS unsigned char* lds) {
;     ...
;         for (int x = 0; x < 16; ++x)
; #pragma unroll
;             for (int y = 0; y < 16; ++y)
;                 if ((x + 1) * (y + 1) <= 16) ck[x][y] = (ordf(unordf(t1[x] & ~0x7Fu) + unordf(t2[y] & ~0x7Fu)) & ~0xFFu) | (unsigned)(255 - (x * 16 + y));
	v_pk_add_f32 v[14:15], v[38:39], v[142:143] op_sel_hi:[0,1]
	v_and_b32_e32 v27, 0x7fffffff, v15
	v_and_b32_e32 v26, 0x7fffffff, v14
	v_xor_b32_e32 v16, -1, v15
	v_pk_add_f32 v[26:27], v[26:27], 0 neg_lo:[1,1] neg_hi:[1,1]
	v_cmp_gt_i32_e32 vcc, 0, v15
	v_xor_b32_e32 v21, -1, v14
	v_and_b32_e32 v39, 0x7fffff80, v35
	v_cndmask_b32_e32 v15, v27, v16, vcc
	v_cmp_gt_i32_e32 vcc, 0, v14
	v_and_b32_e32 v16, 0xffffff80, v24
	v_xor_b32_e32 v16, -1, v16
	v_cndmask_b32_e32 v14, v26, v21, vcc
	v_and_b32_e32 v21, 0xffffff80, v17
	v_cmp_gt_i32_e32 vcc, 0, v24
	v_and_b32_e32 v26, 0x7fffff80, v17
	v_xor_b32_e32 v21, -1, v21
	v_cndmask_b32_e32 v145, v16, v25, vcc
	v_cmp_gt_i32_e32 vcc, 0, v17
	v_and_b32_e32 v12, 0xffffff00, v12
	v_and_b32_e32 v15, 0xffffff00, v15
	v_cndmask_b32_e32 v144, v21, v26, vcc
	v_mov_b32_e32 v21, v145
	v_pk_add_f32 v[16:17], v[36:37], v[20:21] op_sel_hi:[0,1]
	v_and_b32_e32 v25, 0x7fffffff, v17
	v_and_b32_e32 v24, 0x7fffffff, v16
	v_xor_b32_e32 v26, -1, v17
	v_pk_add_f32 v[24:25], v[24:25], 0 neg_lo:[1,1] neg_hi:[1,1]
	v_cmp_gt_i32_e32 vcc, 0, v17
	v_xor_b32_e32 v27, -1, v16
	v_pk_add_f32 v[20:21], v[34:35], v[20:21] op_sel_hi:[0,1]
	v_cndmask_b32_e32 v17, v25, v26, vcc
	v_cmp_gt_i32_e32 vcc, 0, v16
	v_and_b32_e32 v25, 0x7fffffff, v21
	v_xor_b32_e32 v26, -1, v21
	v_cndmask_b32_e32 v16, v24, v27, vcc
	v_and_b32_e32 v24, 0x7fffffff, v20
	v_pk_add_f32 v[24:25], v[24:25], 0 neg_lo:[1,1] neg_hi:[1,1]
	v_cmp_gt_i32_e32 vcc, 0, v21
	v_xor_b32_e32 v27, -1, v20
	v_and_b32_e32 v14, 0xffffff00, v14
	v_cndmask_b32_e32 v21, v25, v26, vcc
	v_cmp_gt_i32_e32 vcc, 0, v20
	v_mov_b32_e32 v25, v38
	v_and_b32_e32 v17, 0xffffff00, v17
	v_cndmask_b32_e32 v20, v24, v27, vcc
	v_mov_b32_e32 v24, v141
	v_pk_add_f32 v[24:25], v[24:25], v[144:145]
	v_and_b32_e32 v16, 0xffffff00, v16
	v_and_b32_e32 v27, 0x7fffffff, v25
	v_and_b32_e32 v26, 0x7fffffff, v24
	v_xor_b32_e32 v31, -1, v25
	v_pk_add_f32 v[26:27], v[26:27], 0 neg_lo:[1,1] neg_hi:[1,1]
	v_cmp_gt_i32_e32 vcc, 0, v25
	v_xor_b32_e32 v37, -1, v24
	v_and_b32_e32 v21, 0xffffff00, v21
	v_cndmask_b32_e32 v25, v27, v31, vcc
	v_cmp_gt_i32_e32 vcc, 0, v24
	v_and_b32_e32 v20, 0xffffff00, v20
	v_and_b32_e32 v25, 0xffffff00, v25
	v_cndmask_b32_e32 v24, v26, v37, vcc
	v_pk_add_f32 v[26:27], v[40:41], v[144:145] op_sel_hi:[1,0]
	v_and_b32_e32 v24, 0xffffff00, v24
	v_and_b32_e32 v147, 0x7fffffff, v27
	v_and_b32_e32 v146, 0x7fffffff, v26
	v_xor_b32_e32 v31, -1, v27
	v_pk_add_f32 v[146:147], v[146:147], 0 neg_lo:[1,1] neg_hi:[1,1]
	v_cmp_gt_i32_e32 vcc, 0, v27
	v_xor_b32_e32 v37, -1, v26
	v_or_b32_e32 v8, 0xf8, v8
	v_cndmask_b32_e32 v27, v147, v31, vcc
	v_cmp_gt_i32_e32 vcc, 0, v26
	v_and_b32_e32 v31, 0xffffff80, v35
	v_xor_b32_e32 v31, -1, v31
	v_cndmask_b32_e32 v26, v146, v37, vcc
	v_cmp_gt_i32_e32 vcc, 0, v35
	v_and_b32_e32 v37, 0xffffff80, v30
	v_xor_b32_e32 v37, -1, v37
	v_cndmask_b32_e32 v147, v31, v39, vcc
	v_mov_b32_e32 v148, v147
	v_cmp_gt_i32_e32 vcc, 0, v30
	v_pk_add_f32 v[30:31], v[36:37], v[148:149] op_sel_hi:[0,1]
	v_and_b32_e32 v36, 0x7fffffff, v30
	v_cndmask_b32_e32 v146, v37, v43, vcc
	v_and_b32_e32 v37, 0x7fffffff, v31
	v_xor_b32_e32 v35, -1, v31
	v_pk_add_f32 v[36:37], v[36:37], 0 neg_lo:[1,1] neg_hi:[1,1]
	v_cmp_gt_i32_e32 vcc, 0, v31
	v_xor_b32_e32 v39, -1, v30
	v_pk_add_f32 v[40:41], v[40:41], v[146:147] op_sel_hi:[1,0]
	v_cndmask_b32_e32 v31, v37, v35, vcc
	v_cmp_gt_i32_e32 vcc, 0, v30
	v_pk_add_f32 v[34:35], v[34:35], v[148:149] op_sel_hi:[0,1]
	v_and_b32_e32 v37, 0x7fffffff, v35
	v_cndmask_b32_e32 v30, v36, v39, vcc
	v_and_b32_e32 v36, 0x7fffffff, v34
	v_xor_b32_e32 v39, -1, v35
	v_pk_add_f32 v[36:37], v[36:37], 0 neg_lo:[1,1] neg_hi:[1,1]
	v_cmp_gt_i32_e32 vcc, 0, v35
	v_xor_b32_e32 v43, -1, v34
	v_and_b32_e32 v27, 0xffffff00, v27
	v_cndmask_b32_e32 v35, v37, v39, vcc
	v_cmp_gt_i32_e32 vcc, 0, v34
	v_and_b32_e32 v26, 0xffffff00, v26
	v_and_b32_e32 v31, 0xffffff00, v31
	v_cndmask_b32_e32 v34, v36, v43, vcc
	v_pk_add_f32 v[36:37], v[38:39], v[148:149] op_sel_hi:[0,1]
	v_and_b32_e32 v39, 0x7fffffff, v37
	v_and_b32_e32 v38, 0x7fffffff, v36
	v_xor_b32_e32 v43, -1, v37
	v_pk_add_f32 v[38:39], v[38:39], 0 neg_lo:[1,1] neg_hi:[1,1]
	v_cmp_gt_i32_e32 vcc, 0, v37
	v_xor_b32_e32 v45, -1, v36
	v_and_b32_e32 v30, 0xffffff00, v30
	v_cndmask_b32_e32 v37, v39, v43, vcc
	v_cmp_gt_i32_e32 vcc, 0, v36
	v_and_b32_e32 v35, 0xffffff00, v35
	v_and_b32_e32 v34, 0xffffff00, v34
	v_cndmask_b32_e32 v36, v38, v45, vcc
	v_pk_mov_b32 v[38:39], v[140:141], v[144:145] op_sel:[1,0]
	v_xor_b32_e32 v140, -1, v46
	v_pk_add_f32 v[38:39], v[38:39], v[146:147]
	v_and_b32_e32 v37, 0xffffff00, v37
	v_and_b32_e32 v145, 0x7fffffff, v39
	v_and_b32_e32 v144, 0x7fffffff, v38
	v_xor_b32_e32 v43, -1, v39
	v_pk_add_f32 v[144:145], v[144:145], 0 neg_lo:[1,1] neg_hi:[1,1]
	v_cmp_gt_i32_e32 vcc, 0, v39
	v_xor_b32_e32 v45, -1, v38
	v_and_b32_e32 v36, 0xffffff00, v36
	v_cndmask_b32_e32 v39, v145, v43, vcc
	v_cmp_gt_i32_e32 vcc, 0, v38
	v_and_b32_e32 v145, 0x7fffffff, v41
	v_xor_b32_e32 v43, -1, v41
	v_cndmask_b32_e32 v38, v144, v45, vcc
	v_and_b32_e32 v144, 0x7fffffff, v40
	v_pk_add_f32 v[144:145], v[144:145], 0 neg_lo:[1,1] neg_hi:[1,1]
	v_cmp_gt_i32_e32 vcc, 0, v41
	v_xor_b32_e32 v45, -1, v40
	v_and_b32_e32 v39, 0xffffff00, v39
	v_cndmask_b32_e32 v41, v145, v43, vcc
	v_cmp_gt_i32_e32 vcc, 0, v40
	v_pk_add_f32 v[42:43], v[42:43], v[142:143] op_sel_hi:[0,1]
	v_and_b32_e32 v145, 0x7fffffff, v43
	v_cndmask_b32_e32 v40, v144, v45, vcc
	v_and_b32_e32 v144, 0x7fffffff, v42
	v_xor_b32_e32 v45, -1, v43
	v_pk_add_f32 v[144:145], v[144:145], 0 neg_lo:[1,1] neg_hi:[1,1]
	v_cmp_gt_i32_e32 vcc, 0, v43
	v_xor_b32_e32 v128, -1, v42
	v_and_b32_e32 v38, 0xffffff00, v38
; DI unsigned ordf(float f) { const unsigned u = __builtin_bit_cast(unsigned, f); return (u & 0x80000000u) ? ~u : (u | 0x80000000u); }
; DI void phase_peer_select(const Args& a, int layer, LAS unsigned char* lds) {
;     ...
;         for (int x = 0; x < 16; ++x)
; #pragma unroll
;             for (int y = 0; y < 16; ++y)
;                 if ((x + 1) * (y + 1) <= 16) ck[x][y] = (ordf(unordf(t1[x] & ~0x7Fu) + unordf(t2[y] & ~0x7Fu)) & ~0xFFu) | (unsigned)(255 - (x * 16 + y));
;         const float scmax = unordf(ck[0][0] & ~0xFFu);
;         int* ip = IDX + m * 128 + h * 16; float* gp = GATE + m * 128 + h * 16;
;         float sum = 0.f;
; #pragma unroll 1
;         for (int k = 0; k < 16; ++k) {
	v_cndmask_b32_e32 v43, v145, v45, vcc
	v_pk_add_f32 v[44:45], v[44:45], v[142:143] op_sel_hi:[0,1]
	v_cmp_gt_i32_e32 vcc, 0, v42
	v_and_b32_e32 v143, 0x7fffffff, v45
	v_and_b32_e32 v142, 0x7fffffff, v44
	v_cndmask_b32_e32 v42, v144, v128, vcc
	v_xor_b32_e32 v128, -1, v45
	v_pk_add_f32 v[142:143], v[142:143], 0 neg_lo:[1,1] neg_hi:[1,1]
	v_cmp_gt_i32_e32 vcc, 0, v45
	v_xor_b32_e32 v144, -1, v44
	v_and_b32_e32 v41, 0xffffff00, v41
	v_cndmask_b32_e32 v45, v143, v128, vcc
	v_cmp_gt_i32_e32 vcc, 0, v44
	v_and_b32_e32 v143, 0x7fffffff, v47
	v_xor_b32_e32 v128, -1, v47
	v_cndmask_b32_e32 v44, v142, v144, vcc
	v_and_b32_e32 v142, 0x7fffffff, v46
	v_pk_add_f32 v[142:143], v[142:143], 0 neg_lo:[1,1] neg_hi:[1,1]
	v_cmp_gt_i32_e32 vcc, 0, v47
	v_and_b32_e32 v144, 0x7fffff80, v33
	v_and_b32_e32 v40, 0xffffff00, v40
	v_cndmask_b32_e32 v47, v143, v128, vcc
	v_cmp_gt_i32_e32 vcc, 0, v46
	v_and_b32_e32 v128, 0xffffff80, v32
	v_xor_b32_e32 v128, -1, v128
	v_cndmask_b32_e32 v46, v142, v140, vcc
	v_and_b32_e32 v140, 0xffffff80, v33
	v_and_b32_e32 v142, 0x7fffff80, v32
	v_cmp_gt_i32_e32 vcc, 0, v32
	v_xor_b32_e32 v140, -1, v140
	v_and_b32_e32 v43, 0xffffff00, v43
	v_cndmask_b32_e32 v143, v128, v142, vcc
	v_cmp_gt_i32_e32 vcc, 0, v33
	v_mov_b32_e32 v128, v141
	v_and_b32_e32 v42, 0xffffff00, v42
	v_cndmask_b32_e32 v142, v140, v144, vcc
	v_pk_add_f32 v[32:33], v[128:129], v[142:143] op_sel_hi:[0,1]
	v_and_b32_e32 v141, 0x7fffffff, v33
	v_and_b32_e32 v140, 0x7fffffff, v32
	v_xor_b32_e32 v142, -1, v33
	v_pk_add_f32 v[140:141], v[140:141], 0 neg_lo:[1,1] neg_hi:[1,1]
	v_cmp_gt_i32_e32 vcc, 0, v33
	v_xor_b32_e32 v143, -1, v32
	v_and_b32_e32 v45, 0xffffff00, v45
	v_cndmask_b32_e32 v33, v141, v142, vcc
	v_cmp_gt_i32_e32 vcc, 0, v32
	v_and_b32_e32 v141, 0xffffff80, v29
	v_and_b32_e32 v142, 0x7fffff80, v28
	v_cndmask_b32_e32 v32, v140, v143, vcc
	v_and_b32_e32 v140, 0xffffff80, v28
	v_xor_b32_e32 v140, -1, v140
	v_cmp_gt_i32_e32 vcc, 0, v28
	v_and_b32_e32 v143, 0x7fffff80, v29
	v_xor_b32_e32 v144, -1, v141
	v_cndmask_b32_e32 v141, v140, v142, vcc
	v_cmp_gt_i32_e32 vcc, 0, v29
	v_and_b32_e32 v44, 0xffffff00, v44
	v_and_b32_e32 v47, 0xffffff00, v47
	v_cndmask_b32_e32 v140, v144, v143, vcc
	v_pk_add_f32 v[28:29], v[128:129], v[140:141] op_sel_hi:[0,1]
	v_and_b32_e32 v141, 0x7fffffff, v29
	v_and_b32_e32 v140, 0x7fffffff, v28
	v_xor_b32_e32 v142, -1, v29
	v_pk_add_f32 v[140:141], v[140:141], 0 neg_lo:[1,1] neg_hi:[1,1]
	v_cmp_gt_i32_e32 vcc, 0, v29
	v_xor_b32_e32 v143, -1, v28
	v_and_b32_e32 v46, 0xffffff00, v46
	v_cndmask_b32_e32 v29, v141, v142, vcc
	v_cmp_gt_i32_e32 vcc, 0, v28
	v_and_b32_e32 v141, 0xffffff80, v23
	v_and_b32_e32 v142, 0x7fffff80, v22
	v_cndmask_b32_e32 v28, v140, v143, vcc
	v_and_b32_e32 v140, 0xffffff80, v22
	v_xor_b32_e32 v140, -1, v140
	v_cmp_gt_i32_e32 vcc, 0, v22
	v_and_b32_e32 v143, 0x7fffff80, v23
	v_xor_b32_e32 v144, -1, v141
	v_cndmask_b32_e32 v141, v140, v142, vcc
	v_cmp_gt_i32_e32 vcc, 0, v23
	v_and_b32_e32 v33, 0xffffff00, v33
	v_and_b32_e32 v32, 0xffffff00, v32
	v_cndmask_b32_e32 v140, v144, v143, vcc
	v_pk_add_f32 v[22:23], v[128:129], v[140:141] op_sel_hi:[0,1]
	v_and_b32_e32 v141, 0x7fffffff, v23
	v_and_b32_e32 v140, 0x7fffffff, v22
	v_xor_b32_e32 v142, -1, v23
	v_pk_add_f32 v[140:141], v[140:141], 0 neg_lo:[1,1] neg_hi:[1,1]
	v_cmp_gt_i32_e32 vcc, 0, v23
	v_xor_b32_e32 v143, -1, v22
	v_and_b32_e32 v29, 0xffffff00, v29
	v_cndmask_b32_e32 v23, v141, v142, vcc
	v_cmp_gt_i32_e32 vcc, 0, v22
	v_and_b32_e32 v141, 0xffffff80, v19
	v_and_b32_e32 v142, 0x7fffff80, v18
	v_cndmask_b32_e32 v22, v140, v143, vcc
	v_and_b32_e32 v140, 0xffffff80, v18
	v_xor_b32_e32 v140, -1, v140
	v_cmp_gt_i32_e32 vcc, 0, v18
	v_and_b32_e32 v143, 0x7fffff80, v19
	v_xor_b32_e32 v144, -1, v141
	v_cndmask_b32_e32 v141, v140, v142, vcc
	v_cmp_gt_i32_e32 vcc, 0, v19
	v_and_b32_e32 v28, 0xffffff00, v28
	v_and_b32_e32 v23, 0xffffff00, v23
	v_cndmask_b32_e32 v140, v144, v143, vcc
	v_pk_add_f32 v[18:19], v[128:129], v[140:141] op_sel_hi:[0,1]
	v_and_b32_e32 v141, 0x7fffffff, v19
	v_and_b32_e32 v140, 0x7fffffff, v18
	v_xor_b32_e32 v128, -1, v19
	v_pk_add_f32 v[140:141], v[140:141], 0 neg_lo:[1,1] neg_hi:[1,1]
	v_cmp_gt_i32_e32 vcc, 0, v19
	v_xor_b32_e32 v142, -1, v18
	v_and_b32_e32 v22, 0xffffff00, v22
	v_cndmask_b32_e32 v19, v141, v128, vcc
	v_cmp_gt_i32_e32 vcc, 0, v18
	v_and_b32_e32 v19, 0xffffff00, v19
	v_and_b32_e32 v128, 0x7fffff00, v131
	v_cndmask_b32_e32 v18, v140, v142, vcc
	v_and_b32_e32 v18, 0xffffff00, v18
	v_bitop3_b32 v140, v131, s0, v131 bitop3:0xcf
	v_cmp_gt_i32_e32 vcc, 0, v131
	v_or_b32_e32 v11, 0xe9, v11
	v_or_b32_e32 v10, 0xe8, v10
	v_or_b32_e32 v49, 0xff, v131
	v_or_b32_e32 v13, 0xef, v13
	v_or_b32_e32 v12, 0xee, v12
	v_or_b32_e32 v15, 0xdf, v15
	v_or_b32_e32 v14, 0xde, v14
	v_or_b32_e32 v17, 0xfb, v17
	v_or_b32_e32 v16, 0xfa, v16
	v_or_b32_e32 v21, 0xeb, v21
	v_or_b32_e32 v20, 0xea, v20
	v_or_b32_e32 v25, 0xdb, v25
	v_or_b32_e32 v24, 0xcf, v24
	v_or_b32_e32 v27, 0xce, v27
	v_or_b32_e32 v26, 0xcd, v26
	v_or_b32_e32 v31, 0xfd, v31
	v_or_b32_e32 v30, 0xfc, v30
	v_or_b32_e32 v35, 0xed, v35
	v_or_b32_e32 v34, 0xec, v34
	v_or_b32_e32 v37, 0xdd, v37
	v_or_b32_e32 v36, 0xdc, v36
	v_or_b32_e32 v39, 0xcc, v39
	v_or_b32_e32 v38, 0xbf, v38
	v_or_b32_e32 v41, 0xbe, v41
	v_or_b32_e32 v40, 0xbd, v40
	v_or_b32_e32 v43, 0xaf, v43
	v_or_b32_e32 v42, 0xae, v42
	v_or_b32_e32 v45, 0x9f, v45
	v_or_b32_e32 v44, 0x9e, v44
	v_or_b32_e32 v47, 0x8f, v47
	v_or_b32_e32 v46, 0x8e, v46
	v_or_b32_e32 v33, 0x7f, v33
	v_or_b32_e32 v32, 0x6f, v32
	v_or_b32_e32 v29, 0x5f, v29
	v_or_b32_e32 v28, 0x4f, v28
	v_or_b32_e32 v23, 63, v23
	v_or_b32_e32 v22, 47, v22
	v_or_b32_e32 v19, 31, v19
	v_or_b32_e32 v18, 15, v18
	v_cndmask_b32_e32 v131, v140, v128, vcc
	v_mov_b32_e32 v128, 0
	s_mov_b64 s[0:1], 0
	s_branch .LBB0_46

; DI void phase_peer_u(const Args& a, int layer, int ci) {
;     ...
;             float glA = 0.f, glB = 0.f, pdA = 0.f, pdB = 0.f, rstdu = 0.f;
;             if (ci == 1) {
;                 glA = GATE[(size_t)m * 128 + lane] * GSUM[(size_t)m * 8 + (lane >> 4)] * (1.f / V_SCALE);
;                 glB = GATE[(size_t)m * 128 + 64 + lane] * GSUM[(size_t)m * 8 + 4 + (lane >> 4)] * (1.f / V_SCALE);
;                 pdA = PD[(size_t)m * 128 + lane]; pdB = PD[(size_t)m * 128 + 64 + lane];
;                 rstdu = __builtin_bit_cast(float, __builtin_amdgcn_readfirstlane(__builtin_bit_cast(int, rsqrtf(wave_sum(lane < 32 ? ((const float*)(ws + WS_RSS))[((size_t)layer * M + m) * 32 + lane] : 0.f) * (1.f / D) + 1e-6f) * (1.f / U_SCALE))));
;             }
;             float rA = 0.f, rB = 0.f;
; #pragma unroll 1
;             for (int g8 = 0; g8 < 16; ++g8) {
;                 u32x4 nxt[8];
;                 if (g8 < 15) gat_loadhu(U, idA, idB, g8 + 1, lo16, nxt); else gat_loadhu(U, idAn, idBn, 0, lo16, nxt);
;                 const float c0 = dots4h(xa, xb, cur[0], cur[1], cur[2], cur[3], lane);
;                 const float c1 = dots4h(xa, xb, cur[4], cur[5], cur[6], cur[7], lane);
;                 const int q4 = (g8 & 7) * 2;
;                 const float cv = (lane >> 2) == q4 ? c0 : c1;
;                 const bool mine = (lane >> 3) == (g8 & 7);
;                 if (ci == 0) { if (g8 < 8) rA = mine ? cv : rA; else rB = mine ? cv : rB; }
;                 else { if (g8 < 8) rA = mine ? gelu_tanh((cv + pdA) * rstdu) * glA : rA; else rB = mine ? gelu_tanh((cv + pdB) * rstdu) * glB : rB; }
; #pragma unroll
;                 for (int j = 0; j < 8; ++j) cur[j] = nxt[j];
;             }
;             if (ci == 0) { PD[(size_t)m * 128 + lane] = rA; PD[(size_t)m * 128 + 64 + lane] = rB; }
;             else { GATE[(size_t)m * 128 + lane] = rA; GATE[(size_t)m * 128 + 64 + lane] = rB; }
.Lpuc_entry:
	v_readlane_b32 s1, v252, 0
	v_readlane_b32 s19, v255, 12
	v_lshrrev_b32_e32 v5, 6, v185
	v_and_b32_e32 v6, 63, v185
	v_lshlrev_b32_e32 v0, 2, v6
	v_and_b32_e32 v1, 31, v6
	v_lshlrev_b32_e32 v1, 2, v1
	v_lshrrev_b32_e32 v3, 5, v6
	v_bfe_u32 v4, v6, 1, 1
	v_lshl_or_b32 v3, v3, 1, v4
	v_bfe_u32 v7, v6, 2, 3
	v_and_b32_e32 v4, 1, v6
	v_lshl_or_b32 v2, v3, 4, v7
	v_lshl_or_b32 v2, v4, 3, v2
	v_lshlrev_b32_e32 v2, 2, v2
	v_lshlrev_b32_e32 v3, 2, v3
	v_readfirstlane_b32 s44, v5
	s_lshl_b32 s45, s1, 3
	s_add_u32 s45, s45, s44
	s_lshl_b32 s46, s45, 13
	s_add_u32 s46, s46, 0x20000000
	s_add_u32 s38, s98, s46
	s_addc_u32 s39, s99, 0
	s_lshl_b32 s46, s45, 13
	s_add_u32 s46, s46, 0x7000000
	s_add_u32 s42, s98, s46
	s_addc_u32 s43, s99, 0
	s_mov_b64 s[16:17], s[42:43]
	s_lshl_b32 s46, s19, 22
	s_lshl_b32 s47, s45, 11
	s_add_u32 s46, s46, s47
	s_add_u32 s46, s46, 0xd800000
	s_add_u32 s40, s98, s46
	s_addc_u32 s41, s99, 0
	s_lshl_b32 s46, s45, 9
	s_add_u32 s46, s46, 0x5e00000
	s_add_u32 s24, s98, s46
	s_addc_u32 s25, s99, 0
	s_mov_b32 s101, 0x39800000
	s_mov_b32 s19, 0x3d372713
	s_mov_b32 s100, 0x200
	s_mov_b32 s0, 0
	s_mov_b64 s[22:23], s[38:39]
	global_load_dword v8, v0, s[22:23]
	global_load_dword v9, v0, s[22:23] offset:256
	s_add_u32 s22, s22, 0x1000000
	s_addc_u32 s23, s23, 0
	global_load_dword v10, v0, s[22:23]
	global_load_dword v11, v0, s[22:23] offset:256
	s_add_u32 s22, s22, 0x1000000
	s_addc_u32 s23, s23, 0
	global_load_dword v12, v0, s[22:23]
	global_load_dword v13, v0, s[22:23] offset:256
	s_add_u32 s22, s22, 0x1000000
	s_addc_u32 s23, s23, 0
	global_load_dword v14, v0, s[22:23]
	global_load_dword v15, v0, s[22:23] offset:256
	s_add_u32 s22, s22, 0x1000000
	s_addc_u32 s23, s23, 0
	global_load_dword v16, v0, s[22:23]
	global_load_dword v17, v0, s[22:23] offset:256
	s_add_u32 s22, s22, 0x1000000
	s_addc_u32 s23, s23, 0
	global_load_dword v18, v0, s[22:23]
	global_load_dword v19, v0, s[22:23] offset:256
	s_add_u32 s22, s22, 0x1000000
	s_addc_u32 s23, s23, 0
	global_load_dword v20, v0, s[22:23]
	global_load_dword v21, v0, s[22:23] offset:256
	s_add_u32 s22, s22, 0x1000000
	s_addc_u32 s23, s23, 0
	global_load_dword v22, v0, s[22:23]
	global_load_dword v23, v0, s[22:23] offset:256
	s_add_u32 s22, s22, 0x1000000
	s_addc_u32 s23, s23, 0
	global_load_dword v24, v0, s[22:23]
	global_load_dword v25, v0, s[22:23] offset:256
	s_add_u32 s22, s22, 0x1000000
	s_addc_u32 s23, s23, 0
	global_load_dword v26, v0, s[22:23]
	global_load_dword v27, v0, s[22:23] offset:256
	s_add_u32 s22, s22, 0x1000000
	s_addc_u32 s23, s23, 0
	global_load_dword v28, v0, s[22:23]
	global_load_dword v29, v0, s[22:23] offset:256
	s_add_u32 s22, s22, 0x1000000
	s_addc_u32 s23, s23, 0
	global_load_dword v30, v0, s[22:23]
	global_load_dword v31, v0, s[22:23] offset:256
	s_add_u32 s22, s22, 0x1000000
	s_addc_u32 s23, s23, 0
	global_load_dword v32, v0, s[22:23]
	global_load_dword v33, v0, s[22:23] offset:256
	s_add_u32 s22, s22, 0x1000000
	s_addc_u32 s23, s23, 0
	global_load_dword v34, v0, s[22:23]
	global_load_dword v35, v0, s[22:23] offset:256
	s_add_u32 s22, s22, 0x1000000
	s_addc_u32 s23, s23, 0
	global_load_dword v36, v0, s[22:23]
	global_load_dword v37, v0, s[22:23] offset:256
	s_add_u32 s22, s22, 0x1000000
	s_addc_u32 s23, s23, 0
	global_load_dword v38, v0, s[22:23]
	global_load_dword v39, v0, s[22:23] offset:256
	global_load_dword v40, v1, s[40:41]
	global_load_dword v41, v2, s[42:43]
	global_load_dword v42, v2, s[42:43] offset:256
	global_load_dword v43, v3, s[24:25]
	global_load_dword v44, v3, s[24:25] offset:16
.Lpuc_loop:
	s_add_u32 s38, s38, s100
	s_addc_u32 s39, s39, 0
	s_lshr_b32 s44, s100, 2
	s_add_u32 s40, s40, s44
	s_addc_u32 s41, s41, 0
	s_lshr_b32 s44, s100, 4
	s_add_u32 s24, s24, s44
	s_addc_u32 s25, s25, 0
	s_add_u32 s42, s42, s100
	s_addc_u32 s43, s43, 0
	s_mov_b64 s[22:23], s[38:39]
	global_load_dword v56, v0, s[22:23]
	global_load_dword v57, v0, s[22:23] offset:256
	s_add_u32 s22, s22, 0x1000000
	s_addc_u32 s23, s23, 0
	global_load_dword v58, v0, s[22:23]
	global_load_dword v59, v0, s[22:23] offset:256
	s_add_u32 s22, s22, 0x1000000
	s_addc_u32 s23, s23, 0
	global_load_dword v60, v0, s[22:23]
	global_load_dword v61, v0, s[22:23] offset:256
	s_add_u32 s22, s22, 0x1000000
	s_addc_u32 s23, s23, 0
	global_load_dword v62, v0, s[22:23]
	global_load_dword v63, v0, s[22:23] offset:256
	s_add_u32 s22, s22, 0x1000000
	s_addc_u32 s23, s23, 0
	global_load_dword v64, v0, s[22:23]
	global_load_dword v65, v0, s[22:23] offset:256
	s_add_u32 s22, s22, 0x1000000
	s_addc_u32 s23, s23, 0
	global_load_dword v66, v0, s[22:23]
	global_load_dword v67, v0, s[22:23] offset:256
	s_add_u32 s22, s22, 0x1000000
	s_addc_u32 s23, s23, 0
	global_load_dword v68, v0, s[22:23]
	global_load_dword v69, v0, s[22:23] offset:256
	s_add_u32 s22, s22, 0x1000000
	s_addc_u32 s23, s23, 0
	global_load_dword v70, v0, s[22:23]
	global_load_dword v71, v0, s[22:23] offset:256
	s_add_u32 s22, s22, 0x1000000
	s_addc_u32 s23, s23, 0
	global_load_dword v72, v0, s[22:23]
	global_load_dword v73, v0, s[22:23] offset:256
	s_add_u32 s22, s22, 0x1000000
	s_addc_u32 s23, s23, 0
	global_load_dword v74, v0, s[22:23]
	global_load_dword v75, v0, s[22:23] offset:256
	s_add_u32 s22, s22, 0x1000000
	s_addc_u32 s23, s23, 0
	global_load_dword v76, v0, s[22:23]
	global_load_dword v77, v0, s[22:23] offset:256
	s_add_u32 s22, s22, 0x1000000
	s_addc_u32 s23, s23, 0
	global_load_dword v78, v0, s[22:23]
	global_load_dword v79, v0, s[22:23] offset:256
	s_add_u32 s22, s22, 0x1000000
	s_addc_u32 s23, s23, 0
	global_load_dword v80, v0, s[22:23]
	global_load_dword v81, v0, s[22:23] offset:256
	s_add_u32 s22, s22, 0x1000000
	s_addc_u32 s23, s23, 0
	global_load_dword v82, v0, s[22:23]
	global_load_dword v83, v0, s[22:23] offset:256
	s_add_u32 s22, s22, 0x1000000
	s_addc_u32 s23, s23, 0
	global_load_dword v84, v0, s[22:23]
	global_load_dword v85, v0, s[22:23] offset:256
	s_add_u32 s22, s22, 0x1000000
	s_addc_u32 s23, s23, 0
	global_load_dword v86, v0, s[22:23]
	global_load_dword v87, v0, s[22:23] offset:256
	global_load_dword v88, v1, s[40:41]
	global_load_dword v89, v2, s[42:43]
	global_load_dword v90, v2, s[42:43] offset:256
	global_load_dword v91, v3, s[24:25]
	global_load_dword v92, v3, s[24:25] offset:16
	s_waitcnt vmcnt(37)
; DI void phase_peer_u(const Args& a, int layer, int ci) {
;     ...
;             if (ci == 1) {
;                 glA = GATE[(size_t)m * 128 + lane] * GSUM[(size_t)m * 8 + (lane >> 4)] * (1.f / V_SCALE);
;                 glB = GATE[(size_t)m * 128 + 64 + lane] * GSUM[(size_t)m * 8 + 4 + (lane >> 4)] * (1.f / V_SCALE);
;                 pdA = PD[(size_t)m * 128 + lane]; pdB = PD[(size_t)m * 128 + 64 + lane];
;                 rstdu = __builtin_bit_cast(float, __builtin_amdgcn_readfirstlane(__builtin_bit_cast(int, rsqrtf(wave_sum(lane < 32 ? ((const float*)(ws + WS_RSS))[((size_t)layer * M + m) * 32 + lane] : 0.f) * (1.f / D) + 1e-6f) * (1.f / U_SCALE))));
;             }
;             float rA = 0.f, rB = 0.f;
; #pragma unroll 1
;             for (int g8 = 0; g8 < 16; ++g8) {
;                 u32x4 nxt[8];
;                 if (g8 < 15) gat_loadhu(U, idA, idB, g8 + 1, lo16, nxt); else gat_loadhu(U, idAn, idBn, 0, lo16, nxt);
;                 const float c0 = dots4h(xa, xb, cur[0], cur[1], cur[2], cur[3], lane);
;                 const float c1 = dots4h(xa, xb, cur[4], cur[5], cur[6], cur[7], lane);
;                 const int q4 = (g8 & 7) * 2;
;                 const float cv = (lane >> 2) == q4 ? c0 : c1;
;                 const bool mine = (lane >> 3) == (g8 & 7);
;                 if (ci == 0) { if (g8 < 8) rA = mine ? cv : rA; else rB = mine ? cv : rB; }
;                 else { if (g8 < 8) rA = mine ? gelu_tanh((cv + pdA) * rstdu) * glA : rA; else rB = mine ? gelu_tanh((cv + pdB) * rstdu) * glB : rB; }
; #pragma unroll
;                 for (int j = 0; j < 8; ++j) cur[j] = nxt[j];
;             }
;             if (ci == 0) { PD[(size_t)m * 128 + lane] = rA; PD[(size_t)m * 128 + 64 + lane] = rB; }
;             else { GATE[(size_t)m * 128 + lane] = rA; GATE[(size_t)m * 128 + 64 + lane] = rB; }
	v_add_f32_e32 v104, v8, v10
	v_add_f32_e32 v104, v104, v12
	v_add_f32_e32 v104, v104, v14
	v_add_f32_e32 v104, v104, v16
	v_add_f32_e32 v104, v104, v18
	v_add_f32_e32 v104, v104, v20
	v_add_f32_e32 v104, v104, v22
	v_add_f32_e32 v104, v104, v24
	v_add_f32_e32 v104, v104, v26
	v_add_f32_e32 v104, v104, v28
	v_add_f32_e32 v104, v104, v30
	v_add_f32_e32 v104, v104, v32
	v_add_f32_e32 v104, v104, v34
	v_add_f32_e32 v104, v104, v36
	v_add_f32_e32 v104, v104, v38
	v_add_f32_e32 v105, v9, v11
	v_add_f32_e32 v105, v105, v13
	v_add_f32_e32 v105, v105, v15
	v_add_f32_e32 v105, v105, v17
	v_add_f32_e32 v105, v105, v19
	v_add_f32_e32 v105, v105, v21
	v_add_f32_e32 v105, v105, v23
	v_add_f32_e32 v105, v105, v25
	v_add_f32_e32 v105, v105, v27
	v_add_f32_e32 v105, v105, v29
	v_add_f32_e32 v105, v105, v31
	v_add_f32_e32 v105, v105, v33
	v_add_f32_e32 v105, v105, v35
	v_add_f32_e32 v105, v105, v37
	v_add_f32_e32 v105, v105, v39
	v_mov_b32_e32 v106, v40
	s_nop 1
	v_add_f32_dpp v106, v106, v106 quad_perm:[1,0,3,2] row_mask:0xf bank_mask:0xf
	s_nop 1
	v_add_f32_dpp v106, v106, v106 quad_perm:[2,3,0,1] row_mask:0xf bank_mask:0xf
	s_nop 1
	v_add_f32_dpp v106, v106, v106 row_half_mirror row_mask:0xf bank_mask:0xf
	s_nop 1
	v_add_f32_dpp v106, v106, v106 row_mirror row_mask:0xf bank_mask:0xf
	s_nop 1
	v_readlane_b32 s44, v106, 0
	v_readlane_b32 s45, v106, 16
	v_readlane_b32 s46, v106, 32
	v_readlane_b32 s47, v106, 48
	s_nop 1
	v_mov_b32_e32 v107, s44
	v_add_f32_e32 v107, s45, v107
	v_add_f32_e32 v107, s46, v107
	v_add_f32_e32 v107, s47, v107
	v_fma_f32 v107, v107, s101, v190
	v_rsq_f32_e32 v107, v107
	s_nop 0
	v_mul_f32_e32 v107, 0x3b000000, v107
	v_mul_f32_e32 v108, 0x3c800000, v43
	v_mul_f32_e32 v109, 0x3c800000, v44
	v_mul_f32_e32 v108, v108, v41
	v_mul_f32_e32 v109, v109, v42
	v_mul_f32_e32 v104, v104, v107
	v_mul_f32_e32 v110, v104, v104
	v_mul_f32_e32 v110, v110, v104
	v_fma_f32 v110, v110, s19, v104
	v_mul_f32_e32 v110, 0x40135761, v110
	v_exp_f32_e32 v110, v110
	s_nop 0
	v_add_f32_e32 v110, 1.0, v110
	v_rcp_f32_e32 v110, v110
	s_nop 0
	v_fma_f32 v111, -v104, v110, v104
	v_mul_f32_e32 v111, v111, v108
	v_mul_f32_e32 v105, v105, v107
	v_mul_f32_e32 v112, v105, v105
	v_mul_f32_e32 v112, v112, v105
	v_fma_f32 v112, v112, s19, v105
	v_mul_f32_e32 v112, 0x40135761, v112
	v_exp_f32_e32 v112, v112
	s_nop 0
	v_add_f32_e32 v112, 1.0, v112
	v_rcp_f32_e32 v112, v112
	s_nop 0
	v_fma_f32 v113, -v105, v112, v105
	v_mul_f32_e32 v113, v113, v109
	global_store_dword v2, v111, s[16:17]
	global_store_dword v2, v113, s[16:17] offset:256
	s_add_u32 s16, s16, 0x200
	s_addc_u32 s17, s17, 0
	s_cmp_eq_u32 s0, 7
	s_cselect_b32 s100, 0, s100
	s_add_u32 s38, s38, s100
	s_addc_u32 s39, s39, 0
	s_lshr_b32 s44, s100, 2
	s_add_u32 s40, s40, s44
	s_addc_u32 s41, s41, 0
	s_lshr_b32 s44, s100, 4
	s_add_u32 s24, s24, s44
	s_addc_u32 s25, s25, 0
	s_add_u32 s42, s42, s100
	s_addc_u32 s43, s43, 0
	s_mov_b64 s[22:23], s[38:39]
	global_load_dword v8, v0, s[22:23]
	global_load_dword v9, v0, s[22:23] offset:256
	s_add_u32 s22, s22, 0x1000000
	s_addc_u32 s23, s23, 0
	global_load_dword v10, v0, s[22:23]
	global_load_dword v11, v0, s[22:23] offset:256
	s_add_u32 s22, s22, 0x1000000
	s_addc_u32 s23, s23, 0
	global_load_dword v12, v0, s[22:23]
	global_load_dword v13, v0, s[22:23] offset:256
	s_add_u32 s22, s22, 0x1000000
	s_addc_u32 s23, s23, 0
	global_load_dword v14, v0, s[22:23]
	global_load_dword v15, v0, s[22:23] offset:256
	s_add_u32 s22, s22, 0x1000000
	s_addc_u32 s23, s23, 0
	global_load_dword v16, v0, s[22:23]
	global_load_dword v17, v0, s[22:23] offset:256
	s_add_u32 s22, s22, 0x1000000
	s_addc_u32 s23, s23, 0
	global_load_dword v18, v0, s[22:23]
	global_load_dword v19, v0, s[22:23] offset:256
	s_add_u32 s22, s22, 0x1000000
	s_addc_u32 s23, s23, 0
	global_load_dword v20, v0, s[22:23]
	global_load_dword v21, v0, s[22:23] offset:256
	s_add_u32 s22, s22, 0x1000000
	s_addc_u32 s23, s23, 0
	global_load_dword v22, v0, s[22:23]
	global_load_dword v23, v0, s[22:23] offset:256
	s_add_u32 s22, s22, 0x1000000
	s_addc_u32 s23, s23, 0
	global_load_dword v24, v0, s[22:23]
	global_load_dword v25, v0, s[22:23] offset:256
	s_add_u32 s22, s22, 0x1000000
	s_addc_u32 s23, s23, 0
	global_load_dword v26, v0, s[22:23]
	global_load_dword v27, v0, s[22:23] offset:256
	s_add_u32 s22, s22, 0x1000000
	s_addc_u32 s23, s23, 0
	global_load_dword v28, v0, s[22:23]
	global_load_dword v29, v0, s[22:23] offset:256
	s_add_u32 s22, s22, 0x1000000
	s_addc_u32 s23, s23, 0
	global_load_dword v30, v0, s[22:23]
	global_load_dword v31, v0, s[22:23] offset:256
	s_add_u32 s22, s22, 0x1000000
	s_addc_u32 s23, s23, 0
	global_load_dword v32, v0, s[22:23]
	global_load_dword v33, v0, s[22:23] offset:256
	s_add_u32 s22, s22, 0x1000000
	s_addc_u32 s23, s23, 0
	global_load_dword v34, v0, s[22:23]
	global_load_dword v35, v0, s[22:23] offset:256
	s_add_u32 s22, s22, 0x1000000
	s_addc_u32 s23, s23, 0
	global_load_dword v36, v0, s[22:23]
	global_load_dword v37, v0, s[22:23] offset:256
	s_add_u32 s22, s22, 0x1000000
	s_addc_u32 s23, s23, 0
	global_load_dword v38, v0, s[22:23]
	global_load_dword v39, v0, s[22:23] offset:256
	global_load_dword v40, v1, s[40:41]
	global_load_dword v41, v2, s[42:43]
	global_load_dword v42, v2, s[42:43] offset:256
	global_load_dword v43, v3, s[24:25]
	global_load_dword v44, v3, s[24:25] offset:16
	s_waitcnt vmcnt(37)
; DI void phase_peer_u(const Args& a, int layer, int ci) {
;     ...
;             if (ci == 1) {
;                 glA = GATE[(size_t)m * 128 + lane] * GSUM[(size_t)m * 8 + (lane >> 4)] * (1.f / V_SCALE);
;                 glB = GATE[(size_t)m * 128 + 64 + lane] * GSUM[(size_t)m * 8 + 4 + (lane >> 4)] * (1.f / V_SCALE);
;                 pdA = PD[(size_t)m * 128 + lane]; pdB = PD[(size_t)m * 128 + 64 + lane];
;                 rstdu = __builtin_bit_cast(float, __builtin_amdgcn_readfirstlane(__builtin_bit_cast(int, rsqrtf(wave_sum(lane < 32 ? ((const float*)(ws + WS_RSS))[((size_t)layer * M + m) * 32 + lane] : 0.f) * (1.f / D) + 1e-6f) * (1.f / U_SCALE))));
;             }
;             float rA = 0.f, rB = 0.f;
; #pragma unroll 1
;             for (int g8 = 0; g8 < 16; ++g8) {
;                 u32x4 nxt[8];
;                 if (g8 < 15) gat_loadhu(U, idA, idB, g8 + 1, lo16, nxt); else gat_loadhu(U, idAn, idBn, 0, lo16, nxt);
;                 const float c0 = dots4h(xa, xb, cur[0], cur[1], cur[2], cur[3], lane);
;                 const float c1 = dots4h(xa, xb, cur[4], cur[5], cur[6], cur[7], lane);
;                 const int q4 = (g8 & 7) * 2;
;                 const float cv = (lane >> 2) == q4 ? c0 : c1;
;                 const bool mine = (lane >> 3) == (g8 & 7);
;                 if (ci == 0) { if (g8 < 8) rA = mine ? cv : rA; else rB = mine ? cv : rB; }
;                 else { if (g8 < 8) rA = mine ? gelu_tanh((cv + pdA) * rstdu) * glA : rA; else rB = mine ? gelu_tanh((cv + pdB) * rstdu) * glB : rB; }
; #pragma unroll
;                 for (int j = 0; j < 8; ++j) cur[j] = nxt[j];
;             }
;             if (ci == 0) { PD[(size_t)m * 128 + lane] = rA; PD[(size_t)m * 128 + 64 + lane] = rB; }
;             else { GATE[(size_t)m * 128 + lane] = rA; GATE[(size_t)m * 128 + 64 + lane] = rB; }
	v_add_f32_e32 v104, v56, v58
	v_add_f32_e32 v104, v104, v60
	v_add_f32_e32 v104, v104, v62
	v_add_f32_e32 v104, v104, v64
	v_add_f32_e32 v104, v104, v66
	v_add_f32_e32 v104, v104, v68
	v_add_f32_e32 v104, v104, v70
	v_add_f32_e32 v104, v104, v72
	v_add_f32_e32 v104, v104, v74
	v_add_f32_e32 v104, v104, v76
	v_add_f32_e32 v104, v104, v78
	v_add_f32_e32 v104, v104, v80
	v_add_f32_e32 v104, v104, v82
	v_add_f32_e32 v104, v104, v84
	v_add_f32_e32 v104, v104, v86
	v_add_f32_e32 v105, v57, v59
	v_add_f32_e32 v105, v105, v61
	v_add_f32_e32 v105, v105, v63
	v_add_f32_e32 v105, v105, v65
	v_add_f32_e32 v105, v105, v67
	v_add_f32_e32 v105, v105, v69
	v_add_f32_e32 v105, v105, v71
	v_add_f32_e32 v105, v105, v73
	v_add_f32_e32 v105, v105, v75
	v_add_f32_e32 v105, v105, v77
	v_add_f32_e32 v105, v105, v79
	v_add_f32_e32 v105, v105, v81
	v_add_f32_e32 v105, v105, v83
	v_add_f32_e32 v105, v105, v85
	v_add_f32_e32 v105, v105, v87
	v_mov_b32_e32 v106, v88
	s_nop 1
	v_add_f32_dpp v106, v106, v106 quad_perm:[1,0,3,2] row_mask:0xf bank_mask:0xf
	s_nop 1
	v_add_f32_dpp v106, v106, v106 quad_perm:[2,3,0,1] row_mask:0xf bank_mask:0xf
	s_nop 1
	v_add_f32_dpp v106, v106, v106 row_half_mirror row_mask:0xf bank_mask:0xf
	s_nop 1
	v_add_f32_dpp v106, v106, v106 row_mirror row_mask:0xf bank_mask:0xf
	s_nop 1
	v_readlane_b32 s44, v106, 0
	v_readlane_b32 s45, v106, 16
	v_readlane_b32 s46, v106, 32
	v_readlane_b32 s47, v106, 48
	s_nop 1
	v_mov_b32_e32 v107, s44
	v_add_f32_e32 v107, s45, v107
	v_add_f32_e32 v107, s46, v107
	v_add_f32_e32 v107, s47, v107
	v_fma_f32 v107, v107, s101, v190
	v_rsq_f32_e32 v107, v107
	s_nop 0
	v_mul_f32_e32 v107, 0x3b000000, v107
	v_mul_f32_e32 v108, 0x3c800000, v91
	v_mul_f32_e32 v109, 0x3c800000, v92
	v_mul_f32_e32 v108, v108, v89
	v_mul_f32_e32 v109, v109, v90
	v_mul_f32_e32 v104, v104, v107
	v_mul_f32_e32 v110, v104, v104
	v_mul_f32_e32 v110, v110, v104
	v_fma_f32 v110, v110, s19, v104
	v_mul_f32_e32 v110, 0x40135761, v110
	v_exp_f32_e32 v110, v110
	s_nop 0
	v_add_f32_e32 v110, 1.0, v110
	v_rcp_f32_e32 v110, v110
	s_nop 0
	v_fma_f32 v111, -v104, v110, v104
	v_mul_f32_e32 v111, v111, v108
	v_mul_f32_e32 v105, v105, v107
	v_mul_f32_e32 v112, v105, v105
	v_mul_f32_e32 v112, v112, v105
	v_fma_f32 v112, v112, s19, v105
	v_mul_f32_e32 v112, 0x40135761, v112
	v_exp_f32_e32 v112, v112
	s_nop 0
	v_add_f32_e32 v112, 1.0, v112
	v_rcp_f32_e32 v112, v112
	s_nop 0
	v_fma_f32 v113, -v105, v112, v105
	v_mul_f32_e32 v113, v113, v109
	global_store_dword v2, v111, s[16:17]
	global_store_dword v2, v113, s[16:17] offset:256
	s_add_u32 s16, s16, 0x200
	s_addc_u32 s17, s17, 0
	s_add_u32 s0, s0, 1
	s_cmp_lt_u32 s0, 8
	s_cbranch_scc1 .Lpuc_loop
	s_waitcnt vmcnt(0)
	s_branch .LBB0_495
